# sigmoid epilogues (ffn1 SwiGLU, gemm_in gates): IEEE f32 division sequence replaced by v_rcp_f32 (f32, 1 ulp), removing ~2000 VALU instructions
# speedup vs baseline: 1.0598x; 1.0188x over previous
; __device__ __forceinline__ unsigned cvt_pk_bf16(float lo, float hi) { unsigned r; asm volatile("v_cvt_pk_bf16_f32 %0, %1, %2" : "=v"(r) : "v"(lo), "v"(hi)); return r; }
; __device__ __forceinline__ float sigmoidf_(float x) { return 1.0f / (1.0f + __builtin_amdgcn_exp2f(-1.4426950408889634f * x)); }
;     __device__ __forceinline__ void operator()(const f32x4 (&acc)[2][2][4][2], const Unit& u, int wr, int wc, int fr, int fq) const {
;     ...
;         const size_t rowb = (size_t)u.pm * BM + wr * 64 + fr; const int col0 = u.pn * HALF + wc * 32 + 8 * fq;
;         const float* bwp = bw + (size_t)(u.pm >> 4) * 5632 + u.pn * BM + wc * 32 + 8 * fq;
;         const f32x4 bg0 = *(const f32x4*)bwp, bg1 = *(const f32x4*)(bwp + 4), bu0 = *(const f32x4*)(bwp + HALF), bu1 = *(const f32x4*)(bwp + HALF + 4);
; #pragma unroll
;         for (int ai = 0; ai < 2; ++ai)
; #pragma unroll
;             for (int m = 0; m < 4; ++m) { const size_t row = rowb + ai * HALF + m * 16; const float r = __builtin_amdgcn_rsqf(ssq2[row] * (1.0f / 1024.0f) + RMS_EPS);
;                 f32x4 g0 = acc[ai][0][m][0] * r + bg0, g1 = acc[ai][0][m][1] * r + bg1; const f32x4 u0 = acc[ai][1][m][0] * r + bu0, u1 = acc[ai][1][m][1] * r + bu1;
; #pragma unroll
;                 for (int i = 0; i < 4; ++i) { g0[i] = g0[i] * sigmoidf_(g0[i]) * u0[i]; g1[i] = g1[i] * sigmoidf_(g1[i]) * u1[i]; }
;                 u32x4 w; w.x = cvt_pk_bf16(g0[0], g0[1]); w.y = cvt_pk_bf16(g0[2], g0[3]); w.z = cvt_pk_bf16(g1[0], g1[1]); w.w = cvt_pk_bf16(g1[2], g1[3]);
;                 *(u32x4*)(O + row * 2816 + col0) = w; }
.LBB0_33:
	s_ashr_i32 s35, s34, 31
	v_mov_b32_e32 v26, v221
	s_lshl_b64 s[38:39], s[34:35], 8
	s_add_u32 s15, s38, s55
	s_addc_u32 s13, s39, s59
	v_and_or_b32 v160, v26, 15, s15
	s_lshl_b32 s15, s63, 7
	v_lshrrev_b32_e32 v26, 1, v26
	s_or_b32 s15, s15, s56
	v_and_b32_e32 v26, 24, v26
	v_or_b32_e32 v162, s15, v26
	s_ashr_i32 s15, s34, 4
	s_mul_hi_i32 s34, s15, 0x5800
	s_mulk_i32 s15, 0x5800
	s_add_u32 s15, s53, s15
	s_addc_u32 s38, s54, s34
	s_lshl_b32 s34, s63, 8
	s_ashr_i32 s35, s34, 31
	s_lshl_b64 s[34:35], s[34:35], 2
	s_add_u32 s15, s15, s34
	v_mov_b32_e32 v161, s13
	s_addc_u32 s35, s38, s35
	s_add_u32 s34, s15, s62
	v_lshlrev_b64 v[158:159], 2, v[160:161]
	s_addc_u32 s35, s35, 0
	v_lshlrev_b32_e32 v30, 2, v26
	v_lshl_add_u64 v[156:157], s[8:9], 0, v[158:159]
	global_load_dwordx4 v[50:53], v30, s[34:35] offset:16
	global_load_dwordx4 v[54:57], v30, s[34:35]
	global_load_dwordx4 v[26:29], v30, s[34:35] offset:528
	s_nop 0
	global_load_dwordx4 v[30:33], v30, s[34:35] offset:512
	s_movk_i32 s15, 0x1600
	global_load_dword v161, v[156:157], off
	v_ashrrev_i32_e32 v163, 31, v162
	s_waitcnt vmcnt(0)
	v_fmamk_f32 v161, v161, 0x3a800000, v231
	v_rsq_f32_e32 v164, v161
	s_nop 0
	v_pk_fma_f32 v[142:143], v[142:143], v[164:165], v[54:55] op_sel_hi:[1,0,1]
	s_nop 0
	v_mul_f32_e32 v161, 0xbfb8aa3b, v142
	v_exp_f32_e32 v161, v161
	v_pk_fma_f32 v[138:139], v[138:139], v[164:165], v[50:51] op_sel_hi:[1,0,1]
	v_fma_f32 v134, v134, v164, v30
	v_fma_f32 v130, v130, v164, v26
	v_add_f32_e32 v161, 1.0, v161
	v_fma_f32 v135, v135, v164, v31
	v_pk_fma_f32 v[144:145], v[144:145], v[164:165], v[56:57] op_sel_hi:[1,0,1]
	v_fma_f32 v131, v131, v164, v27
	v_rcp_f32_e32 v161, v161
	s_nop 0
	v_mul_f32_e32 v142, v142, v161
	v_mul_f32_e32 v134, v134, v142
	v_mul_f32_e32 v142, 0xbfb8aa3b, v138
	v_exp_f32_e32 v142, v142
	v_pk_fma_f32 v[140:141], v[140:141], v[164:165], v[52:53] op_sel_hi:[1,0,1]
	v_fma_f32 v136, v136, v164, v32
	v_fma_f32 v132, v132, v164, v28
	v_add_f32_e32 v142, 1.0, v142
	v_fma_f32 v137, v137, v164, v33
	v_fma_f32 v133, v133, v164, v29
	v_rcp_f32_e32 v142, v142
	s_nop 0
	v_mul_f32_e32 v138, v138, v142
	v_mul_f32_e32 v130, v130, v138
	v_mul_f32_e32 v138, 0xbfb8aa3b, v143
	v_exp_f32_e32 v138, v138
	s_nop 0
	v_add_f32_e32 v138, 1.0, v138
	v_rcp_f32_e32 v138, v138
	s_nop 0
	v_mul_f32_e32 v138, v143, v138
	v_mul_f32_e32 v135, v135, v138
	v_mul_f32_e32 v138, 0xbfb8aa3b, v139
	v_exp_f32_e32 v138, v138
	s_nop 0
	v_add_f32_e32 v138, 1.0, v138
	v_rcp_f32_e32 v138, v138
	s_nop 0
	v_mul_f32_e32 v138, v139, v138
	v_mul_f32_e32 v131, v131, v138
	v_mul_f32_e32 v138, 0xbfb8aa3b, v144
	v_exp_f32_e32 v138, v138
	s_nop 0
	v_add_f32_e32 v138, 1.0, v138
	v_rcp_f32_e32 v138, v138
	s_nop 0
	v_mul_f32_e32 v138, v144, v138
	v_mul_f32_e32 v136, v136, v138
	v_mul_f32_e32 v138, 0xbfb8aa3b, v140
	v_exp_f32_e32 v138, v138
	s_nop 0
	v_add_f32_e32 v138, 1.0, v138
	v_rcp_f32_e32 v138, v138
	s_nop 0
	v_mul_f32_e32 v138, v140, v138
	v_mul_f32_e32 v138, v132, v138
	v_mul_f32_e32 v132, 0xbfb8aa3b, v145
	v_exp_f32_e32 v132, v132
	s_nop 0
	v_add_f32_e32 v132, 1.0, v132
	v_rcp_f32_e32 v132, v132
	s_nop 0
	v_mul_f32_e32 v132, v145, v132
	v_mul_f32_e32 v137, v137, v132
	v_mul_f32_e32 v132, 0xbfb8aa3b, v141
	v_exp_f32_e32 v132, v132
	s_nop 0
	v_add_f32_e32 v132, 1.0, v132
	v_rcp_f32_e32 v132, v132
	s_nop 0
	v_mul_f32_e32 v132, v141, v132
	v_mul_f32_e32 v139, v133, v132
	v_cvt_pk_bf16_f32 v132, v134, v135
	v_cvt_pk_bf16_f32 v133, v136, v137
	v_cvt_pk_bf16_f32 v134, v130, v131
	v_mov_b64_e32 v[130:131], s[6:7]
	v_mad_u64_u32 v[130:131], s[34:35], v160, s15, v[130:131]
	v_mov_b32_e32 v136, 0x1600
	v_mad_i32_i24 v131, s13, v136, v131
	v_lshl_add_u64 v[130:131], v[162:163], 1, v[130:131]
	v_cvt_pk_bf16_f32 v135, v138, v139
	global_store_dwordx4 v[130:131], v[132:135], off
	s_mov_b32 s13, 0x16000
	s_nop 0
	v_or_b32_e32 v132, 64, v158
	v_mov_b32_e32 v133, v159
	v_lshl_add_u64 v[132:133], s[8:9], 0, v[132:133]
	global_load_dword v132, v[132:133], off
	s_waitcnt vmcnt(0)
	v_fmamk_f32 v132, v132, 0x3a800000, v231
	v_rsq_f32_e32 v132, v132
	s_nop 0
	v_pk_fma_f32 v[126:127], v[126:127], v[132:133], v[54:55] op_sel_hi:[1,0,1]
	v_pk_fma_f32 v[128:129], v[128:129], v[132:133], v[56:57] op_sel_hi:[1,0,1]
	v_pk_fma_f32 v[124:125], v[124:125], v[132:133], v[52:53] op_sel_hi:[1,0,1]
	v_pk_fma_f32 v[122:123], v[122:123], v[132:133], v[50:51] op_sel_hi:[1,0,1]
	v_mul_f32_e32 v133, 0xbfb8aa3b, v126
	v_exp_f32_e32 v133, v133
	v_fma_f32 v118, v118, v132, v30
	v_fma_f32 v114, v114, v132, v26
	v_fma_f32 v119, v119, v132, v31
	v_add_f32_e32 v133, 1.0, v133
	v_fma_f32 v115, v115, v132, v27
	v_fma_f32 v120, v120, v132, v32
	v_fma_f32 v116, v116, v132, v28
	v_rcp_f32_e32 v133, v133
	s_nop 0
	v_mul_f32_e32 v126, v126, v133
	v_mul_f32_e32 v118, v118, v126
	v_mul_f32_e32 v126, 0xbfb8aa3b, v122
	v_exp_f32_e32 v126, v126
	v_fma_f32 v121, v121, v132, v33
	v_fma_f32 v117, v117, v132, v29
	v_add_f32_e32 v126, 1.0, v126
	v_rcp_f32_e32 v126, v126
	s_nop 0
	v_mul_f32_e32 v122, v122, v126
	v_mul_f32_e32 v122, v114, v122
	v_mul_f32_e32 v114, 0xbfb8aa3b, v127
	v_exp_f32_e32 v114, v114
	s_nop 0
	v_add_f32_e32 v114, 1.0, v114
	v_rcp_f32_e32 v114, v114
	s_nop 0
	v_mul_f32_e32 v114, v127, v114
	v_mul_f32_e32 v114, v119, v114
	v_mul_f32_e32 v119, 0xbfb8aa3b, v123
	v_exp_f32_e32 v119, v119
	v_cvt_pk_bf16_f32 v114, v118, v114
	s_nop 0
	v_add_f32_e32 v119, 1.0, v119
	v_rcp_f32_e32 v119, v119
	s_nop 0
	v_mul_f32_e32 v119, v123, v119
	v_mul_f32_e32 v119, v115, v119
	v_mul_f32_e32 v115, 0xbfb8aa3b, v128
	v_exp_f32_e32 v115, v115
	s_nop 0
	v_add_f32_e32 v115, 1.0, v115
	v_rcp_f32_e32 v115, v115
	s_nop 0
	v_mul_f32_e32 v115, v128, v115
	v_mul_f32_e32 v115, v120, v115
	v_mul_f32_e32 v120, 0xbfb8aa3b, v124
	v_exp_f32_e32 v120, v120
	s_nop 0
	v_add_f32_e32 v120, 1.0, v120
	v_rcp_f32_e32 v120, v120
	s_nop 0
	v_mul_f32_e32 v120, v124, v120
	v_mul_f32_e32 v120, v116, v120
	v_mul_f32_e32 v116, 0xbfb8aa3b, v129
	v_exp_f32_e32 v116, v116
	s_nop 0
	v_add_f32_e32 v116, 1.0, v116
	v_rcp_f32_e32 v116, v116
	s_nop 0
	v_mul_f32_e32 v116, v129, v116
	v_mul_f32_e32 v116, v121, v116
	v_mul_f32_e32 v121, 0xbfb8aa3b, v125
	v_exp_f32_e32 v121, v121
	v_cvt_pk_bf16_f32 v115, v115, v116
	v_cvt_pk_bf16_f32 v116, v122, v119
	s_nop 0
	v_add_f32_e32 v121, 1.0, v121
	v_rcp_f32_e32 v121, v121
	s_nop 0
	v_mul_f32_e32 v121, v125, v121
	v_add_co_u32_e32 v118, vcc, s13, v130
	v_mul_f32_e32 v117, v117, v121
	s_nop 0
	v_addc_co_u32_e32 v119, vcc, 0, v131, vcc
	v_cvt_pk_bf16_f32 v117, v120, v117
	global_store_dwordx4 v[118:119], v[114:117], off
	s_mov_b32 s13, 0x2c000
	s_nop 0
	v_or_b32_e32 v114, 0x80, v158
	v_mov_b32_e32 v115, v159
	v_lshl_add_u64 v[114:115], s[8:9], 0, v[114:115]
	global_load_dword v114, v[114:115], off
	v_or_b32_e32 v158, 0xc0, v158
	s_waitcnt vmcnt(0)
; __device__ __forceinline__ unsigned cvt_pk_bf16(float lo, float hi) { unsigned r; asm volatile("v_cvt_pk_bf16_f32 %0, %1, %2" : "=v"(r) : "v"(lo), "v"(hi)); return r; }
; __device__ __forceinline__ float sigmoidf_(float x) { return 1.0f / (1.0f + __builtin_amdgcn_exp2f(-1.4426950408889634f * x)); }
;     __device__ __forceinline__ void operator()(const f32x4 (&acc)[2][2][4][2], const Unit& u, int wr, int wc, int fr, int fq) const {
;     ...
;             for (int m = 0; m < 4; ++m) { const size_t row = rowb + ai * HALF + m * 16; const float r = __builtin_amdgcn_rsqf(ssq2[row] * (1.0f / 1024.0f) + RMS_EPS);
;                 f32x4 g0 = acc[ai][0][m][0] * r + bg0, g1 = acc[ai][0][m][1] * r + bg1; const f32x4 u0 = acc[ai][1][m][0] * r + bu0, u1 = acc[ai][1][m][1] * r + bu1;
; #pragma unroll
;                 for (int i = 0; i < 4; ++i) { g0[i] = g0[i] * sigmoidf_(g0[i]) * u0[i]; g1[i] = g1[i] * sigmoidf_(g1[i]) * u1[i]; }
;                 u32x4 w; w.x = cvt_pk_bf16(g0[0], g0[1]); w.y = cvt_pk_bf16(g0[2], g0[3]); w.z = cvt_pk_bf16(g1[0], g1[1]); w.w = cvt_pk_bf16(g1[2], g1[3]);
;                 *(u32x4*)(O + row * 2816 + col0) = w; }
	v_fmamk_f32 v114, v114, 0x3a800000, v231
	v_rsq_f32_e32 v114, v114
	s_nop 0
	v_pk_fma_f32 v[110:111], v[110:111], v[114:115], v[54:55] op_sel_hi:[1,0,1]
	v_pk_fma_f32 v[112:113], v[112:113], v[114:115], v[56:57] op_sel_hi:[1,0,1]
	v_pk_fma_f32 v[108:109], v[108:109], v[114:115], v[52:53] op_sel_hi:[1,0,1]
	v_pk_fma_f32 v[106:107], v[106:107], v[114:115], v[50:51] op_sel_hi:[1,0,1]
	v_mul_f32_e32 v115, 0xbfb8aa3b, v110
	v_exp_f32_e32 v115, v115
	v_fma_f32 v102, v102, v114, v30
	v_fma_f32 v98, v98, v114, v26
	v_fma_f32 v103, v103, v114, v31
	v_add_f32_e32 v115, 1.0, v115
	v_fma_f32 v99, v99, v114, v27
	v_fma_f32 v104, v104, v114, v32
	v_fma_f32 v100, v100, v114, v28
	v_rcp_f32_e32 v115, v115
	s_nop 0
	v_mul_f32_e32 v110, v110, v115
	v_mul_f32_e32 v102, v102, v110
	v_mul_f32_e32 v110, 0xbfb8aa3b, v106
	v_exp_f32_e32 v110, v110
	v_fma_f32 v105, v105, v114, v33
	v_fma_f32 v101, v101, v114, v29
	v_add_f32_e32 v110, 1.0, v110
	v_rcp_f32_e32 v110, v110
	s_nop 0
	v_mul_f32_e32 v106, v106, v110
	v_mul_f32_e32 v106, v98, v106
	v_mul_f32_e32 v98, 0xbfb8aa3b, v111
	v_exp_f32_e32 v98, v98
	s_nop 0
	v_add_f32_e32 v98, 1.0, v98
	v_rcp_f32_e32 v98, v98
	s_nop 0
	v_mul_f32_e32 v98, v111, v98
	v_mul_f32_e32 v98, v103, v98
	v_mul_f32_e32 v103, 0xbfb8aa3b, v107
	v_exp_f32_e32 v103, v103
	v_cvt_pk_bf16_f32 v98, v102, v98
	s_nop 0
	v_add_f32_e32 v103, 1.0, v103
	v_rcp_f32_e32 v103, v103
	s_nop 0
	v_mul_f32_e32 v103, v107, v103
	v_mul_f32_e32 v103, v99, v103
	v_mul_f32_e32 v99, 0xbfb8aa3b, v112
	v_exp_f32_e32 v99, v99
	s_nop 0
	v_add_f32_e32 v99, 1.0, v99
	v_rcp_f32_e32 v99, v99
	s_nop 0
	v_mul_f32_e32 v99, v112, v99
	v_mul_f32_e32 v99, v104, v99
	v_mul_f32_e32 v104, 0xbfb8aa3b, v108
	v_exp_f32_e32 v104, v104
	s_nop 0
	v_add_f32_e32 v104, 1.0, v104
	v_rcp_f32_e32 v104, v104
	s_nop 0
	v_mul_f32_e32 v104, v108, v104
	v_mul_f32_e32 v104, v100, v104
	v_mul_f32_e32 v100, 0xbfb8aa3b, v113
	v_exp_f32_e32 v100, v100
	s_nop 0
	v_add_f32_e32 v100, 1.0, v100
	v_rcp_f32_e32 v100, v100
	s_nop 0
	v_mul_f32_e32 v100, v113, v100
	v_mul_f32_e32 v100, v105, v100
	v_mul_f32_e32 v105, 0xbfb8aa3b, v109
	v_exp_f32_e32 v105, v105
	v_cvt_pk_bf16_f32 v99, v99, v100
	v_cvt_pk_bf16_f32 v100, v106, v103
	s_nop 0
	v_add_f32_e32 v105, 1.0, v105
	v_rcp_f32_e32 v105, v105
	s_nop 0
	v_mul_f32_e32 v105, v109, v105
	v_add_co_u32_e32 v102, vcc, s13, v130
	v_mul_f32_e32 v101, v101, v105
	s_nop 0
	v_addc_co_u32_e32 v103, vcc, 0, v131, vcc
	v_cvt_pk_bf16_f32 v101, v104, v101
	global_store_dwordx4 v[102:103], v[98:101], off
	s_mov_b32 s13, 0x42000
	s_nop 0
	v_lshl_add_u64 v[98:99], s[8:9], 0, v[158:159]
	global_load_dword v98, v[98:99], off
	s_waitcnt vmcnt(0)
	v_fmamk_f32 v98, v98, 0x3a800000, v231
	v_rsq_f32_e32 v98, v98
	s_nop 0
	v_pk_fma_f32 v[94:95], v[94:95], v[98:99], v[54:55] op_sel_hi:[1,0,1]
	v_pk_fma_f32 v[96:97], v[96:97], v[98:99], v[56:57] op_sel_hi:[1,0,1]
	v_pk_fma_f32 v[92:93], v[92:93], v[98:99], v[52:53] op_sel_hi:[1,0,1]
	v_pk_fma_f32 v[90:91], v[90:91], v[98:99], v[50:51] op_sel_hi:[1,0,1]
	v_mul_f32_e32 v99, 0xbfb8aa3b, v94
	v_exp_f32_e32 v99, v99
	v_fma_f32 v86, v86, v98, v30
	v_fma_f32 v82, v82, v98, v26
	v_fma_f32 v87, v87, v98, v31
	v_add_f32_e32 v99, 1.0, v99
	v_fma_f32 v83, v83, v98, v27
	v_fma_f32 v88, v88, v98, v32
	v_fma_f32 v84, v84, v98, v28
	v_rcp_f32_e32 v99, v99
	s_nop 0
	v_mul_f32_e32 v94, v94, v99
	v_mul_f32_e32 v86, v86, v94
	v_mul_f32_e32 v94, 0xbfb8aa3b, v90
	v_exp_f32_e32 v94, v94
	v_fma_f32 v89, v89, v98, v33
	v_fma_f32 v85, v85, v98, v29
	v_add_f32_e32 v94, 1.0, v94
	v_rcp_f32_e32 v94, v94
	s_nop 0
	v_mul_f32_e32 v90, v90, v94
	v_mul_f32_e32 v90, v82, v90
	v_mul_f32_e32 v82, 0xbfb8aa3b, v95
	v_exp_f32_e32 v82, v82
	s_nop 0
	v_add_f32_e32 v82, 1.0, v82
	v_rcp_f32_e32 v82, v82
	s_nop 0
	v_mul_f32_e32 v82, v95, v82
	v_mul_f32_e32 v82, v87, v82
	v_mul_f32_e32 v87, 0xbfb8aa3b, v91
	v_exp_f32_e32 v87, v87
	v_cvt_pk_bf16_f32 v82, v86, v82
	s_nop 0
	v_add_f32_e32 v87, 1.0, v87
	v_rcp_f32_e32 v87, v87
	s_nop 0
	v_mul_f32_e32 v87, v91, v87
	v_mul_f32_e32 v87, v83, v87
	v_mul_f32_e32 v83, 0xbfb8aa3b, v96
	v_exp_f32_e32 v83, v83
	s_nop 0
	v_add_f32_e32 v83, 1.0, v83
	v_rcp_f32_e32 v83, v83
	s_nop 0
	v_mul_f32_e32 v83, v96, v83
	v_mul_f32_e32 v83, v88, v83
	v_mul_f32_e32 v88, 0xbfb8aa3b, v92
	v_exp_f32_e32 v88, v88
	s_nop 0
	v_add_f32_e32 v88, 1.0, v88
	v_rcp_f32_e32 v88, v88
	s_nop 0
	v_mul_f32_e32 v88, v92, v88
	v_mul_f32_e32 v88, v84, v88
	v_mul_f32_e32 v84, 0xbfb8aa3b, v97
	v_exp_f32_e32 v84, v84
	s_nop 0
	v_add_f32_e32 v84, 1.0, v84
	v_rcp_f32_e32 v84, v84
	s_nop 0
	v_mul_f32_e32 v84, v97, v84
	v_mul_f32_e32 v84, v89, v84
	v_mul_f32_e32 v89, 0xbfb8aa3b, v93
	v_exp_f32_e32 v89, v89
	v_cvt_pk_bf16_f32 v83, v83, v84
	v_cvt_pk_bf16_f32 v84, v90, v87
	s_nop 0
	v_add_f32_e32 v89, 1.0, v89
	v_rcp_f32_e32 v89, v89
	s_nop 0
	v_mul_f32_e32 v89, v93, v89
	v_add_co_u32_e32 v86, vcc, s13, v130
	v_mul_f32_e32 v85, v85, v89
	s_nop 0
	v_addc_co_u32_e32 v87, vcc, 0, v131, vcc
	v_cvt_pk_bf16_f32 v85, v88, v85
	global_store_dwordx4 v[86:87], v[82:85], off
	global_load_dword v82, v[156:157], off offset:512
	s_mov_b32 s13, 0xc6000
	s_waitcnt vmcnt(0)
; __device__ __forceinline__ unsigned cvt_pk_bf16(float lo, float hi) { unsigned r; asm volatile("v_cvt_pk_bf16_f32 %0, %1, %2" : "=v"(r) : "v"(lo), "v"(hi)); return r; }
; __device__ __forceinline__ float sigmoidf_(float x) { return 1.0f / (1.0f + __builtin_amdgcn_exp2f(-1.4426950408889634f * x)); }
;     __device__ __forceinline__ void operator()(const f32x4 (&acc)[2][2][4][2], const Unit& u, int wr, int wc, int fr, int fq) const {
;     ...
;             for (int m = 0; m < 4; ++m) { const size_t row = rowb + ai * HALF + m * 16; const float r = __builtin_amdgcn_rsqf(ssq2[row] * (1.0f / 1024.0f) + RMS_EPS);
;                 f32x4 g0 = acc[ai][0][m][0] * r + bg0, g1 = acc[ai][0][m][1] * r + bg1; const f32x4 u0 = acc[ai][1][m][0] * r + bu0, u1 = acc[ai][1][m][1] * r + bu1;
; #pragma unroll
;                 for (int i = 0; i < 4; ++i) { g0[i] = g0[i] * sigmoidf_(g0[i]) * u0[i]; g1[i] = g1[i] * sigmoidf_(g1[i]) * u1[i]; }
;                 u32x4 w; w.x = cvt_pk_bf16(g0[0], g0[1]); w.y = cvt_pk_bf16(g0[2], g0[3]); w.z = cvt_pk_bf16(g1[0], g1[1]); w.w = cvt_pk_bf16(g1[2], g1[3]);
;                 *(u32x4*)(O + row * 2816 + col0) = w; }
	v_fmamk_f32 v82, v82, 0x3a800000, v231
	v_rsq_f32_e32 v82, v82
	s_nop 0
	v_pk_fma_f32 v[78:79], v[78:79], v[82:83], v[54:55] op_sel_hi:[1,0,1]
	v_pk_fma_f32 v[80:81], v[80:81], v[82:83], v[56:57] op_sel_hi:[1,0,1]
	v_pk_fma_f32 v[76:77], v[76:77], v[82:83], v[52:53] op_sel_hi:[1,0,1]
	v_pk_fma_f32 v[74:75], v[74:75], v[82:83], v[50:51] op_sel_hi:[1,0,1]
	v_mul_f32_e32 v83, 0xbfb8aa3b, v78
	v_exp_f32_e32 v83, v83
	v_fma_f32 v70, v70, v82, v30
	v_fma_f32 v62, v62, v82, v26
	v_fma_f32 v71, v71, v82, v31
	v_add_f32_e32 v83, 1.0, v83
	v_fma_f32 v63, v63, v82, v27
	v_fma_f32 v72, v72, v82, v32
	v_fma_f32 v64, v64, v82, v28
	v_rcp_f32_e32 v83, v83
	s_nop 0
	v_mul_f32_e32 v78, v78, v83
	v_mul_f32_e32 v70, v70, v78
	v_mul_f32_e32 v78, 0xbfb8aa3b, v74
	v_exp_f32_e32 v78, v78
	v_fma_f32 v73, v73, v82, v33
	v_fma_f32 v65, v65, v82, v29
	v_add_f32_e32 v78, 1.0, v78
	v_rcp_f32_e32 v78, v78
	s_nop 0
	v_mul_f32_e32 v74, v74, v78
	v_mul_f32_e32 v74, v62, v74
	v_mul_f32_e32 v62, 0xbfb8aa3b, v79
	v_exp_f32_e32 v62, v62
	s_nop 0
	v_add_f32_e32 v62, 1.0, v62
	v_rcp_f32_e32 v62, v62
	s_nop 0
	v_mul_f32_e32 v62, v79, v62
	v_mul_f32_e32 v62, v71, v62
	v_mul_f32_e32 v71, 0xbfb8aa3b, v75
	v_exp_f32_e32 v71, v71
	v_cvt_pk_bf16_f32 v62, v70, v62
	s_nop 0
	v_add_f32_e32 v71, 1.0, v71
	v_rcp_f32_e32 v71, v71
	s_nop 0
	v_mul_f32_e32 v71, v75, v71
	v_mul_f32_e32 v71, v63, v71
	v_mul_f32_e32 v63, 0xbfb8aa3b, v80
	v_exp_f32_e32 v63, v63
	s_nop 0
	v_add_f32_e32 v63, 1.0, v63
	v_rcp_f32_e32 v63, v63
	s_nop 0
	v_mul_f32_e32 v63, v80, v63
	v_mul_f32_e32 v63, v72, v63
	v_mul_f32_e32 v72, 0xbfb8aa3b, v76
	v_exp_f32_e32 v72, v72
	s_nop 0
	v_add_f32_e32 v72, 1.0, v72
	v_rcp_f32_e32 v72, v72
	s_nop 0
	v_mul_f32_e32 v72, v76, v72
	v_mul_f32_e32 v72, v64, v72
	v_mul_f32_e32 v64, 0xbfb8aa3b, v81
	v_exp_f32_e32 v64, v64
	s_nop 0
	v_add_f32_e32 v64, 1.0, v64
	v_rcp_f32_e32 v64, v64
	s_nop 0
	v_mul_f32_e32 v64, v81, v64
	v_mul_f32_e32 v64, v73, v64
	v_mul_f32_e32 v73, 0xbfb8aa3b, v77
	v_exp_f32_e32 v73, v73
	v_cvt_pk_bf16_f32 v63, v63, v64
	v_cvt_pk_bf16_f32 v64, v74, v71
	s_nop 0
	v_add_f32_e32 v73, 1.0, v73
	v_rcp_f32_e32 v73, v73
	s_nop 0
	v_mul_f32_e32 v73, v77, v73
	v_add_co_u32_e32 v70, vcc, s95, v130
	v_mul_f32_e32 v65, v65, v73
	s_nop 0
	v_addc_co_u32_e32 v71, vcc, 0, v131, vcc
	v_cvt_pk_bf16_f32 v65, v72, v65
	global_store_dwordx4 v[70:71], v[62:65], off
	global_load_dword v62, v[156:157], off offset:576
	s_waitcnt vmcnt(0)
	v_fmamk_f32 v62, v62, 0x3a800000, v231
	v_rsq_f32_e32 v62, v62
	s_nop 0
	v_pk_fma_f32 v[66:67], v[66:67], v[62:63], v[54:55] op_sel_hi:[1,0,1]
	v_pk_fma_f32 v[64:65], v[68:69], v[62:63], v[56:57] op_sel_hi:[1,0,1]
	v_pk_fma_f32 v[60:61], v[60:61], v[62:63], v[52:53] op_sel_hi:[1,0,1]
	v_pk_fma_f32 v[58:59], v[58:59], v[62:63], v[50:51] op_sel_hi:[1,0,1]
	v_mul_f32_e32 v63, 0xbfb8aa3b, v66
	v_exp_f32_e32 v63, v63
	v_fma_f32 v46, v46, v62, v30
	v_fma_f32 v38, v38, v62, v26
	v_fma_f32 v47, v47, v62, v31
	v_add_f32_e32 v63, 1.0, v63
	v_fma_f32 v39, v39, v62, v27
	v_fma_f32 v48, v48, v62, v32
	v_fma_f32 v40, v40, v62, v28
	v_rcp_f32_e32 v63, v63
	s_nop 0
	v_mul_f32_e32 v63, v66, v63
	v_mul_f32_e32 v46, v46, v63
	v_mul_f32_e32 v63, 0xbfb8aa3b, v58
	v_exp_f32_e32 v63, v63
	v_fma_f32 v49, v49, v62, v33
	v_fma_f32 v41, v41, v62, v29
	v_add_f32_e32 v63, 1.0, v63
	v_rcp_f32_e32 v63, v63
	s_nop 0
	v_mul_f32_e32 v58, v58, v63
	v_mul_f32_e32 v58, v38, v58
	v_mul_f32_e32 v38, 0xbfb8aa3b, v67
	v_exp_f32_e32 v38, v38
	s_nop 0
	v_add_f32_e32 v38, 1.0, v38
	v_rcp_f32_e32 v38, v38
	s_nop 0
	v_mul_f32_e32 v38, v67, v38
	v_mul_f32_e32 v38, v47, v38
	v_mul_f32_e32 v47, 0xbfb8aa3b, v59
	v_exp_f32_e32 v47, v47
	v_cvt_pk_bf16_f32 v38, v46, v38
	s_nop 0
	v_add_f32_e32 v47, 1.0, v47
	v_rcp_f32_e32 v47, v47
	s_nop 0
	v_mul_f32_e32 v47, v59, v47
	v_mul_f32_e32 v47, v39, v47
	v_mul_f32_e32 v39, 0xbfb8aa3b, v64
	v_exp_f32_e32 v39, v39
	s_nop 0
	v_add_f32_e32 v39, 1.0, v39
	v_rcp_f32_e32 v39, v39
	s_nop 0
	v_mul_f32_e32 v39, v64, v39
	v_mul_f32_e32 v39, v48, v39
	v_mul_f32_e32 v48, 0xbfb8aa3b, v60
	v_exp_f32_e32 v48, v48
	s_nop 0
	v_add_f32_e32 v48, 1.0, v48
	v_rcp_f32_e32 v48, v48
	s_nop 0
	v_mul_f32_e32 v48, v60, v48
	v_mul_f32_e32 v48, v40, v48
	v_mul_f32_e32 v40, 0xbfb8aa3b, v65
	v_exp_f32_e32 v40, v40
	s_nop 0
	v_add_f32_e32 v40, 1.0, v40
	v_rcp_f32_e32 v40, v40
	s_nop 0
	v_mul_f32_e32 v40, v65, v40
	v_mul_f32_e32 v40, v49, v40
	v_mul_f32_e32 v49, 0xbfb8aa3b, v61
	v_exp_f32_e32 v49, v49
	v_cvt_pk_bf16_f32 v39, v39, v40
	v_cvt_pk_bf16_f32 v40, v58, v47
	s_nop 0
	v_add_f32_e32 v49, 1.0, v49
	v_rcp_f32_e32 v49, v49
	s_nop 0
	v_mul_f32_e32 v49, v61, v49
	v_add_co_u32_e32 v46, vcc, s13, v130
	v_mul_f32_e32 v41, v41, v49
	s_nop 0
	v_addc_co_u32_e32 v47, vcc, 0, v131, vcc
	v_cvt_pk_bf16_f32 v41, v48, v41
	global_store_dwordx4 v[46:47], v[38:41], off
	global_load_dword v38, v[156:157], off offset:640
	s_mov_b32 s13, 0xdc000
	s_waitcnt vmcnt(0)
; __device__ __forceinline__ unsigned cvt_pk_bf16(float lo, float hi) { unsigned r; asm volatile("v_cvt_pk_bf16_f32 %0, %1, %2" : "=v"(r) : "v"(lo), "v"(hi)); return r; }
; __device__ __forceinline__ float sigmoidf_(float x) { return 1.0f / (1.0f + __builtin_amdgcn_exp2f(-1.4426950408889634f * x)); }
;     __device__ __forceinline__ void operator()(const f32x4 (&acc)[2][2][4][2], const Unit& u, int wr, int wc, int fr, int fq) const {
;     ...
;             for (int m = 0; m < 4; ++m) { const size_t row = rowb + ai * HALF + m * 16; const float r = __builtin_amdgcn_rsqf(ssq2[row] * (1.0f / 1024.0f) + RMS_EPS);
;                 f32x4 g0 = acc[ai][0][m][0] * r + bg0, g1 = acc[ai][0][m][1] * r + bg1; const f32x4 u0 = acc[ai][1][m][0] * r + bu0, u1 = acc[ai][1][m][1] * r + bu1;
; #pragma unroll
;                 for (int i = 0; i < 4; ++i) { g0[i] = g0[i] * sigmoidf_(g0[i]) * u0[i]; g1[i] = g1[i] * sigmoidf_(g1[i]) * u1[i]; }
;                 u32x4 w; w.x = cvt_pk_bf16(g0[0], g0[1]); w.y = cvt_pk_bf16(g0[2], g0[3]); w.z = cvt_pk_bf16(g1[0], g1[1]); w.w = cvt_pk_bf16(g1[2], g1[3]);
;                 *(u32x4*)(O + row * 2816 + col0) = w; }
	v_fmamk_f32 v38, v38, 0x3a800000, v231
	v_rsq_f32_e32 v38, v38
	s_nop 0
	v_pk_fma_f32 v[42:43], v[42:43], v[38:39], v[54:55] op_sel_hi:[1,0,1]
	v_pk_fma_f32 v[40:41], v[44:45], v[38:39], v[56:57] op_sel_hi:[1,0,1]
	v_pk_fma_f32 v[36:37], v[36:37], v[38:39], v[52:53] op_sel_hi:[1,0,1]
	v_pk_fma_f32 v[34:35], v[34:35], v[38:39], v[50:51] op_sel_hi:[1,0,1]
	v_mul_f32_e32 v39, 0xbfb8aa3b, v42
	v_exp_f32_e32 v39, v39
	v_fma_f32 v22, v22, v38, v30
	v_fma_f32 v14, v14, v38, v26
	v_fma_f32 v23, v23, v38, v31
	v_add_f32_e32 v39, 1.0, v39
	v_fma_f32 v15, v15, v38, v27
	v_fma_f32 v24, v24, v38, v32
	v_fma_f32 v16, v16, v38, v28
	v_rcp_f32_e32 v39, v39
	s_nop 0
	v_mul_f32_e32 v39, v42, v39
	v_mul_f32_e32 v22, v22, v39
	v_mul_f32_e32 v39, 0xbfb8aa3b, v34
	v_exp_f32_e32 v39, v39
	v_fma_f32 v25, v25, v38, v33
	v_fma_f32 v17, v17, v38, v29
	v_add_f32_e32 v39, 1.0, v39
	v_rcp_f32_e32 v39, v39
	s_nop 0
	v_mul_f32_e32 v34, v34, v39
	v_mul_f32_e32 v34, v14, v34
	v_mul_f32_e32 v14, 0xbfb8aa3b, v43
	v_exp_f32_e32 v14, v14
	s_nop 0
	v_add_f32_e32 v14, 1.0, v14
	v_rcp_f32_e32 v14, v14
	s_nop 0
	v_mul_f32_e32 v14, v43, v14
	v_mul_f32_e32 v14, v23, v14
	v_mul_f32_e32 v23, 0xbfb8aa3b, v35
	v_exp_f32_e32 v23, v23
	v_cvt_pk_bf16_f32 v14, v22, v14
	s_nop 0
	v_add_f32_e32 v23, 1.0, v23
	v_rcp_f32_e32 v23, v23
	s_nop 0
	v_mul_f32_e32 v23, v35, v23
	v_mul_f32_e32 v23, v15, v23
	v_mul_f32_e32 v15, 0xbfb8aa3b, v40
	v_exp_f32_e32 v15, v15
	s_nop 0
	v_add_f32_e32 v15, 1.0, v15
	v_rcp_f32_e32 v15, v15
	s_nop 0
	v_mul_f32_e32 v15, v40, v15
	v_mul_f32_e32 v15, v24, v15
	v_mul_f32_e32 v24, 0xbfb8aa3b, v36
	v_exp_f32_e32 v24, v24
	s_nop 0
	v_add_f32_e32 v24, 1.0, v24
	v_rcp_f32_e32 v24, v24
	s_nop 0
	v_mul_f32_e32 v24, v36, v24
	v_mul_f32_e32 v24, v16, v24
	v_mul_f32_e32 v16, 0xbfb8aa3b, v41
	v_exp_f32_e32 v16, v16
	s_nop 0
	v_add_f32_e32 v16, 1.0, v16
	v_rcp_f32_e32 v16, v16
	s_nop 0
	v_mul_f32_e32 v16, v41, v16
	v_mul_f32_e32 v16, v25, v16
	v_mul_f32_e32 v25, 0xbfb8aa3b, v37
	v_exp_f32_e32 v25, v25
	v_cvt_pk_bf16_f32 v15, v15, v16
	v_cvt_pk_bf16_f32 v16, v34, v23
	s_nop 0
	v_add_f32_e32 v25, 1.0, v25
	v_rcp_f32_e32 v25, v25
	s_nop 0
	v_mul_f32_e32 v25, v37, v25
	v_add_co_u32_e32 v22, vcc, s13, v130
	v_mul_f32_e32 v17, v17, v25
	s_nop 0
	v_addc_co_u32_e32 v23, vcc, 0, v131, vcc
	v_cvt_pk_bf16_f32 v17, v24, v17
	global_store_dwordx4 v[22:23], v[14:17], off
	global_load_dword v14, v[156:157], off offset:704
	s_waitcnt vmcnt(0)
	v_fmamk_f32 v14, v14, 0x3a800000, v231
	v_rsq_f32_e32 v14, v14
	s_nop 0
	v_pk_fma_f32 v[18:19], v[18:19], v[14:15], v[54:55] op_sel_hi:[1,0,1]
	v_pk_fma_f32 v[16:17], v[20:21], v[14:15], v[56:57] op_sel_hi:[1,0,1]
	v_pk_fma_f32 v[12:13], v[12:13], v[14:15], v[52:53] op_sel_hi:[1,0,1]
	v_pk_fma_f32 v[10:11], v[10:11], v[14:15], v[50:51] op_sel_hi:[1,0,1]
	v_mul_f32_e32 v15, 0xbfb8aa3b, v18
	v_exp_f32_e32 v15, v15
	v_fma_f32 v6, v6, v14, v30
	v_fma_f32 v2, v2, v14, v26
	v_fma_f32 v7, v7, v14, v31
	v_add_f32_e32 v15, 1.0, v15
	v_fma_f32 v3, v3, v14, v27
	v_fma_f32 v8, v8, v14, v32
	v_fma_f32 v4, v4, v14, v28
	v_rcp_f32_e32 v15, v15
	s_nop 0
	v_mul_f32_e32 v15, v18, v15
	v_mul_f32_e32 v6, v6, v15
	v_mul_f32_e32 v15, 0xbfb8aa3b, v10
	v_exp_f32_e32 v15, v15
	v_fmac_f32_e32 v33, v9, v14
	v_mul_f32_e32 v9, 0xbfb8aa3b, v13
	v_exp_f32_e32 v9, v9
	v_add_f32_e32 v15, 1.0, v15
	v_add_f32_e32 v9, 1.0, v9
	v_fmac_f32_e32 v29, v5, v14
	v_rcp_f32_e32 v15, v15
	s_nop 0
	v_mul_f32_e32 v10, v10, v15
	v_mul_f32_e32 v10, v2, v10
	v_mul_f32_e32 v2, 0xbfb8aa3b, v19
	v_exp_f32_e32 v2, v2
	s_nop 0
	v_add_f32_e32 v2, 1.0, v2
	v_rcp_f32_e32 v2, v2
	s_nop 0
	v_mul_f32_e32 v2, v19, v2
	v_mul_f32_e32 v2, v7, v2
	v_mul_f32_e32 v7, 0xbfb8aa3b, v11
	v_exp_f32_e32 v7, v7
	v_cvt_pk_bf16_f32 v2, v6, v2
	s_nop 0
	v_add_f32_e32 v7, 1.0, v7
	v_rcp_f32_e32 v7, v7
	s_nop 0
	v_mul_f32_e32 v7, v11, v7
	v_mul_f32_e32 v7, v3, v7
	v_mul_f32_e32 v3, 0xbfb8aa3b, v16
	v_exp_f32_e32 v3, v3
	s_nop 0
	v_add_f32_e32 v3, 1.0, v3
	v_rcp_f32_e32 v3, v3
	s_nop 0
	v_mul_f32_e32 v3, v16, v3
	v_mul_f32_e32 v3, v8, v3
	v_mul_f32_e32 v8, 0xbfb8aa3b, v12
	v_exp_f32_e32 v8, v8
	s_nop 0
	v_add_f32_e32 v8, 1.0, v8
	v_rcp_f32_e32 v8, v8
	s_nop 0
	v_mul_f32_e32 v8, v12, v8
	v_mul_f32_e32 v8, v4, v8
	v_mul_f32_e32 v4, 0xbfb8aa3b, v17
	v_exp_f32_e32 v4, v4
	s_nop 0
	v_add_f32_e32 v4, 1.0, v4
	v_rcp_f32_e32 v4, v4
	s_nop 0
	v_div_scale_f32 v11, s[34:35], v9, v9, 1.0
	v_rcp_f32_e32 v12, v11
	v_mul_f32_e32 v4, v17, v4
	v_mul_f32_e32 v4, v33, v4
	v_cvt_pk_bf16_f32 v3, v3, v4
	v_fma_f32 v15, -v11, v12, 1.0
	v_fmac_f32_e32 v12, v15, v12
	v_div_scale_f32 v15, vcc, 1.0, v9, 1.0
	v_mul_f32_e32 v16, v15, v12
	v_fma_f32 v17, -v11, v16, v15
	v_fmac_f32_e32 v16, v17, v12
	v_fma_f32 v11, -v11, v16, v15
	v_div_fmas_f32 v11, v11, v12, v16
	v_div_fixup_f32 v9, v11, v9, 1.0
	v_add_co_u32_e32 v6, vcc, 0xf2000, v130
	v_mul_f32_e32 v9, v13, v9
	v_cvt_pk_bf16_f32 v4, v10, v7
	s_nop 0
	v_addc_co_u32_e32 v7, vcc, 0, v131, vcc
	v_mul_f32_e32 v5, v29, v9
	s_mov_b64 s[34:35], -1
	s_andn2_b64 vcc, exec, s[40:41]
	v_cvt_pk_bf16_f32 v5, v8, v5
	global_store_dwordx4 v[6:7], v[2:5], off
	s_cbranch_vccnz .LBB0_26
	s_andn2_b64 vcc, exec, s[2:3]
	s_cbranch_vccnz .LBB0_25
	s_barrier
	s_branch .LBB0_25

; __device__ __forceinline__ float sigmoidf_(float x) { return 1.0f / (1.0f + __builtin_amdgcn_exp2f(-1.4426950408889634f * x)); }
; #define EPIIN_PACK(w, a, b) do { (w).x = cvt_pk_bf16((a)[0], (a)[1]); (w).y = cvt_pk_bf16((a)[2], (a)[3]); (w).z = cvt_pk_bf16((b)[0], (b)[1]); (w).w = cvt_pk_bf16((b)[2], (b)[3]); } while (0)
;     __device__ __forceinline__ void operator()(const f32x4 (&acc_)[2][2][4][2], const Unit& u, int wr, int wc, int fr, int fq) const {
;     ...
;         const int pn = u.pn; const size_t rowb = (size_t)u.pm * BM + wr * 64 + fr;
;         f32x4 bv[2][2]; float r8[2][4];
;         { const float* bwp = bw + (size_t)(u.pm >> 4) * 4096 + pn * BM + wc * 32 + fq * 8;
; #pragma unroll
;           for (int bj = 0; bj < 2; ++bj)
; #pragma unroll
;               for (int n = 0; n < 2; ++n) bv[bj][n] = *(const f32x4*)(bwp + bj * HALF + n * 4);
; #pragma unroll
;           for (int ai = 0; ai < 2; ++ai)
; #pragma unroll
;               for (int m = 0; m < 4; ++m) r8[ai][m] = __builtin_amdgcn_rsqf(ssq1[rowb + ai * HALF + m * 16] * (1.0f / 1024.0f) + RMS_EPS); }
;     ...
;         } else {
; #pragma unroll
;             for (int ai = 0; ai < 2; ++ai)
; #pragma unroll
;                 for (int m = 0; m < 4; ++m) { const size_t row = rowb + ai * HALF + m * 16;
; #pragma unroll
;                     for (int bj = 0; bj < 2; ++bj) { f32x4 a = EPIIN_VAL(ai, bj, m, 0), b = EPIIN_VAL(ai, bj, m, 1);
; #pragma unroll
;                         for (int i = 0; i < 4; ++i) { a[i] = sigmoidf_(a[i]); b[i] = sigmoidf_(b[i]); }
;                         u32x4 w; EPIIN_PACK(w, a, b);
;                         *(u32x4*)(GATES + row * 2048 + (pn - 8) * 256 + bj * HALF + wc * 32 + fq * 8) = w; } }
.LBB0_555:
	s_ashr_i32 s6, s2, 4
	s_ashr_i32 s7, s6, 31
	s_ashr_i32 s3, s2, 31
	s_lshl_b64 s[6:7], s[6:7], 14
	s_add_u32 s30, s12, s6
	s_addc_u32 s34, s13, s7
	s_lshl_b32 s68, s46, 8
	s_ashr_i32 s69, s68, 31
	s_lshl_b64 s[6:7], s[68:69], 2
	s_add_u32 s6, s30, s6
	s_addc_u32 s7, s34, s7
	s_lshl_b32 s30, s50, 2
	s_add_u32 s6, s6, s30
	s_addc_u32 s7, s7, 0
	s_lshl_b64 s[2:3], s[2:3], 8
	s_add_u32 s42, s2, s49
	v_mov_b32_e32 v0, v221
	s_addc_u32 s43, s3, s95
	v_mov_b32_e32 v159, s43
	v_bfe_u32 v165, v0, 4, 2
	v_and_or_b32 v158, v0, 15, s42
	v_lshlrev_b32_e32 v94, 5, v165
	v_lshl_add_u64 v[176:177], v[158:159], 2, s[16:17]
	global_load_dwordx4 v[106:109], v94, s[6:7] offset:16
	global_load_dwordx4 v[110:113], v94, s[6:7]
	global_load_dwordx4 v[90:93], v94, s[6:7] offset:528
	s_nop 0
	global_load_dwordx4 v[94:97], v94, s[6:7] offset:512
	v_lshlrev_b32_e32 v167, 3, v165
	global_load_dword v0, v[176:177], off
	s_mov_b64 s[2:3], -1
	s_cmp_gt_i32 s46, 1
	s_waitcnt vmcnt(0)
	v_fmamk_f32 v0, v0, 0x3a800000, v231
	v_rsq_f32_e32 v174, v0
	global_load_dword v0, v[176:177], off offset:64
	s_waitcnt vmcnt(0)
	v_fmamk_f32 v0, v0, 0x3a800000, v231
	v_rsq_f32_e32 v172, v0
	global_load_dword v0, v[176:177], off offset:128
	s_waitcnt vmcnt(0)
	v_fmamk_f32 v0, v0, 0x3a800000, v231
	v_rsq_f32_e32 v170, v0
	global_load_dword v0, v[176:177], off offset:192
	s_waitcnt vmcnt(0)
	v_fmamk_f32 v0, v0, 0x3a800000, v231
	v_rsq_f32_e32 v168, v0
	global_load_dword v0, v[176:177], off offset:512
	s_waitcnt vmcnt(0)
	v_fmamk_f32 v0, v0, 0x3a800000, v231
	v_rsq_f32_e32 v166, v0
	global_load_dword v0, v[176:177], off offset:576
	s_waitcnt vmcnt(0)
	v_fmamk_f32 v0, v0, 0x3a800000, v231
	v_rsq_f32_e32 v164, v0
	global_load_dword v0, v[176:177], off offset:640
	s_waitcnt vmcnt(0)
	v_fmamk_f32 v0, v0, 0x3a800000, v231
	v_rsq_f32_e32 v162, v0
	global_load_dword v0, v[176:177], off offset:704
	s_waitcnt vmcnt(0)
	v_fmamk_f32 v0, v0, 0x3a800000, v231
	v_rsq_f32_e32 v160, v0
	s_cbranch_scc0 .LBB0_565
	s_cmp_gt_u32 s46, 5
	s_cbranch_scc0 .LBB0_562
	s_cmp_lt_u32 s46, 8
	s_cbranch_scc1 .LBB0_559
	v_pk_fma_f32 v[182:183], v[142:143], v[174:175], v[110:111] op_sel_hi:[1,0,1]
	v_pk_fma_f32 v[180:181], v[144:145], v[174:175], v[112:113] op_sel_hi:[1,0,1]
	v_mul_f32_e32 v0, 0xbfb8aa3b, v182
	v_exp_f32_e32 v0, v0
	v_pk_fma_f32 v[178:179], v[140:141], v[174:175], v[108:109] op_sel_hi:[1,0,1]
	v_pk_fma_f32 v[184:185], v[138:139], v[174:175], v[106:107] op_sel_hi:[1,0,1]
	v_mul_f32_e32 v178, 0xbfb8aa3b, v178
	v_add_f32_e32 v0, 1.0, v0
	v_exp_f32_e32 v178, v178
	v_lshlrev_b64 v[176:177], 12, v[158:159]
	s_add_i32 s30, s68, 0xfffff800
	v_rcp_f32_e32 v0, v0
	s_nop 0
	v_mul_f32_e32 v169, 0xbfb8aa3b, v184
	v_exp_f32_e32 v169, v169
	v_add_f32_e32 v178, 1.0, v178
	v_add_f32_e32 v169, 1.0, v169
	v_rcp_f32_e32 v169, v169
	s_nop 0
	v_mul_f32_e32 v171, 0xbfb8aa3b, v183
	v_exp_f32_e32 v171, v171
	s_nop 0
	v_add_f32_e32 v171, 1.0, v171
	v_rcp_f32_e32 v171, v171
	s_nop 0
	v_mul_f32_e32 v173, 0xbfb8aa3b, v185
	v_exp_f32_e32 v173, v173
	s_nop 0
	v_add_f32_e32 v173, 1.0, v173
	v_rcp_f32_e32 v173, v173
	s_nop 0
	v_mul_f32_e32 v175, 0xbfb8aa3b, v180
	v_exp_f32_e32 v175, v175
	s_nop 0
	v_add_f32_e32 v175, 1.0, v175
	v_rcp_f32_e32 v175, v175
	s_nop 0
	v_rcp_f32_e32 v182, v178
	s_nop 0
	v_mul_f32_e32 v178, 0xbfb8aa3b, v181
	v_exp_f32_e32 v178, v178
	s_nop 0
	v_add_f32_e32 v178, 1.0, v178
	v_rcp_f32_e32 v180, v178
	s_nop 0
	v_mul_f32_e32 v178, 0xbfb8aa3b, v179
	v_exp_f32_e32 v178, v178
	s_nop 0
	v_add_f32_e32 v178, 1.0, v178
	v_readlane_b32 s2, v255, 47
	v_readlane_b32 s3, v255, 48
	v_lshl_add_u64 v[176:177], s[2:3], 0, v[176:177]
	v_rcp_f32_e32 v181, v178
	s_nop 0
	v_lshl_add_u64 v[176:177], s[30:31], 1, v[176:177]
	s_lshl_b32 s30, s50, 1
	v_cvt_pk_bf16_f32 v178, v0, v171
	v_cvt_pk_bf16_f32 v179, v175, v180
	v_cvt_pk_bf16_f32 v180, v169, v173
	v_cvt_pk_bf16_f32 v181, v182, v181
	v_lshl_add_u64 v[176:177], v[176:177], 0, s[30:31]
	v_lshlrev_b32_e32 v0, 1, v167
	v_pk_fma_f32 v[182:183], v[134:135], v[174:175], v[94:95] op_sel_hi:[1,0,1]
	v_lshl_add_u64 v[176:177], v[176:177], 0, v[0:1]
	v_mul_f32_e32 v0, 0xbfb8aa3b, v182
	v_exp_f32_e32 v0, v0
	global_store_dwordx4 v[176:177], v[178:181], off
	v_pk_fma_f32 v[184:185], v[130:131], v[174:175], v[90:91] op_sel_hi:[1,0,1]
	v_add_f32_e32 v0, 1.0, v0
	v_div_scale_f32 v169, s[2:3], v0, v0, 1.0
	v_rcp_f32_e32 v171, v169
	v_pk_fma_f32 v[180:181], v[136:137], v[174:175], v[96:97] op_sel_hi:[1,0,1]
	v_pk_fma_f32 v[178:179], v[132:133], v[174:175], v[92:93] op_sel_hi:[1,0,1]
	v_fma_f32 v173, -v169, v171, 1.0
	v_fmac_f32_e32 v171, v173, v171
	v_div_scale_f32 v173, vcc, 1.0, v0, 1.0
	v_mul_f32_e32 v175, v173, v171
	v_fma_f32 v182, -v169, v175, v173
	v_fmac_f32_e32 v175, v182, v171
	v_fma_f32 v169, -v169, v175, v173
	v_div_fmas_f32 v169, v169, v171, v175
	v_div_fixup_f32 v0, v169, v0, 1.0
	v_mul_f32_e32 v169, 0xbfb8aa3b, v184
	v_exp_f32_e32 v169, v169
	v_mul_f32_e32 v178, 0xbfb8aa3b, v178
	v_exp_f32_e32 v178, v178
	v_add_f32_e32 v169, 1.0, v169
	v_add_f32_e32 v178, 1.0, v178
	v_rcp_f32_e32 v169, v169
	s_nop 0
	v_mul_f32_e32 v171, 0xbfb8aa3b, v183
	v_exp_f32_e32 v171, v171
	s_nop 0
	v_add_f32_e32 v171, 1.0, v171
	v_rcp_f32_e32 v171, v171
	s_nop 0
	v_mul_f32_e32 v173, 0xbfb8aa3b, v185
	v_exp_f32_e32 v173, v173
	s_nop 0
	v_add_f32_e32 v173, 1.0, v173
	v_rcp_f32_e32 v173, v173
	s_nop 0
	v_mul_f32_e32 v175, 0xbfb8aa3b, v180
	v_exp_f32_e32 v175, v175
	s_nop 0
	v_add_f32_e32 v175, 1.0, v175
	v_rcp_f32_e32 v175, v175
	s_nop 0
	v_rcp_f32_e32 v182, v178
	s_nop 0
	v_mul_f32_e32 v178, 0xbfb8aa3b, v181
	v_exp_f32_e32 v178, v178
	s_nop 0
	v_add_f32_e32 v178, 1.0, v178
	v_rcp_f32_e32 v180, v178
; __device__ __forceinline__ float sigmoidf_(float x) { return 1.0f / (1.0f + __builtin_amdgcn_exp2f(-1.4426950408889634f * x)); }
; #define EPIIN_PACK(w, a, b) do { (w).x = cvt_pk_bf16((a)[0], (a)[1]); (w).y = cvt_pk_bf16((a)[2], (a)[3]); (w).z = cvt_pk_bf16((b)[0], (b)[1]); (w).w = cvt_pk_bf16((b)[2], (b)[3]); } while (0)
;     __device__ __forceinline__ void operator()(const f32x4 (&acc_)[2][2][4][2], const Unit& u, int wr, int wc, int fr, int fq) const {
;     ...
;         } else {
; #pragma unroll
;             for (int ai = 0; ai < 2; ++ai)
; #pragma unroll
;                 for (int m = 0; m < 4; ++m) { const size_t row = rowb + ai * HALF + m * 16;
; #pragma unroll
;                     for (int bj = 0; bj < 2; ++bj) { f32x4 a = EPIIN_VAL(ai, bj, m, 0), b = EPIIN_VAL(ai, bj, m, 1);
; #pragma unroll
;                         for (int i = 0; i < 4; ++i) { a[i] = sigmoidf_(a[i]); b[i] = sigmoidf_(b[i]); }
;                         u32x4 w; EPIIN_PACK(w, a, b);
;                         *(u32x4*)(GATES + row * 2048 + (pn - 8) * 256 + bj * HALF + wc * 32 + fq * 8) = w; } }
	s_nop 0
	v_mul_f32_e32 v178, 0xbfb8aa3b, v179
	v_exp_f32_e32 v178, v178
	s_nop 0
	v_add_f32_e32 v178, 1.0, v178
	v_rcp_f32_e32 v181, v178
	s_nop 0
	v_cvt_pk_bf16_f32 v178, v0, v171
	v_cvt_pk_bf16_f32 v179, v175, v180
	v_cvt_pk_bf16_f32 v180, v169, v173
	v_cvt_pk_bf16_f32 v181, v182, v181
	v_pk_fma_f32 v[182:183], v[126:127], v[172:173], v[110:111] op_sel_hi:[1,0,1]
	global_store_dwordx4 v[176:177], v[178:181], off offset:256
	v_mul_f32_e32 v0, 0xbfb8aa3b, v182
	v_exp_f32_e32 v0, v0
	v_pk_fma_f32 v[180:181], v[128:129], v[172:173], v[112:113] op_sel_hi:[1,0,1]
	v_pk_fma_f32 v[178:179], v[124:125], v[172:173], v[108:109] op_sel_hi:[1,0,1]
	v_pk_fma_f32 v[184:185], v[122:123], v[172:173], v[106:107] op_sel_hi:[1,0,1]
	v_add_f32_e32 v0, 1.0, v0
	v_mul_f32_e32 v178, 0xbfb8aa3b, v178
	v_exp_f32_e32 v178, v178
	v_mul_f32_e32 v179, 0xbfb8aa3b, v179
	v_rcp_f32_e32 v0, v0
	s_nop 0
	v_mul_f32_e32 v169, 0xbfb8aa3b, v184
	v_exp_f32_e32 v169, v169
	v_add_f32_e32 v178, 1.0, v178
	v_exp_f32_e32 v179, v179
	v_add_f32_e32 v169, 1.0, v169
	v_add_f32_e32 v179, 1.0, v179
	v_rcp_f32_e32 v169, v169
	s_nop 0
	v_mul_f32_e32 v171, 0xbfb8aa3b, v183
	v_exp_f32_e32 v171, v171
	s_nop 0
	v_add_f32_e32 v171, 1.0, v171
	v_rcp_f32_e32 v171, v171
	s_nop 0
	v_mul_f32_e32 v173, 0xbfb8aa3b, v185
	v_exp_f32_e32 v173, v173
	s_nop 0
	v_add_f32_e32 v173, 1.0, v173
	v_rcp_f32_e32 v173, v173
	s_nop 0
	v_mul_f32_e32 v175, 0xbfb8aa3b, v180
	v_exp_f32_e32 v175, v175
	v_pk_fma_f32 v[186:187], v[114:115], v[172:173], v[90:91] op_sel_hi:[1,0,1]
	v_add_f32_e32 v175, 1.0, v175
	v_rcp_f32_e32 v175, v175
	s_nop 0
	v_rcp_f32_e32 v178, v178
	s_nop 0
	v_mul_f32_e32 v180, 0xbfb8aa3b, v181
	v_exp_f32_e32 v180, v180
	s_nop 0
	v_add_f32_e32 v180, 1.0, v180
	v_rcp_f32_e32 v181, v180
	s_nop 0
	s_mov_b64 s[2:3], 0x10000
	v_rcp_f32_e32 v179, v179
	s_nop 0
	v_cvt_pk_bf16_f32 v180, v0, v171
	v_cvt_pk_bf16_f32 v181, v175, v181
	v_cvt_pk_bf16_f32 v182, v169, v173
	v_cvt_pk_bf16_f32 v183, v178, v179
	v_lshl_add_u64 v[178:179], v[176:177], 0, s[2:3]
	s_mov_b32 s2, 0x10000
	v_add_co_u32_e32 v184, vcc, s2, v176
	s_nop 1
	v_addc_co_u32_e32 v185, vcc, 0, v177, vcc
	global_store_dwordx4 v[184:185], v[180:183], off
	v_pk_fma_f32 v[184:185], v[118:119], v[172:173], v[94:95] op_sel_hi:[1,0,1]
	s_nop 0
	v_mul_f32_e32 v0, 0xbfb8aa3b, v184
	v_exp_f32_e32 v0, v0
	v_pk_fma_f32 v[182:183], v[120:121], v[172:173], v[96:97] op_sel_hi:[1,0,1]
	v_pk_fma_f32 v[180:181], v[116:117], v[172:173], v[92:93] op_sel_hi:[1,0,1]
	v_add_f32_e32 v0, 1.0, v0
	v_mul_f32_e32 v180, 0xbfb8aa3b, v180
	v_exp_f32_e32 v180, v180
	v_rcp_f32_e32 v0, v0
	s_nop 0
	v_mul_f32_e32 v169, 0xbfb8aa3b, v186
	v_exp_f32_e32 v169, v169
	v_add_f32_e32 v180, 1.0, v180
	v_add_f32_e32 v169, 1.0, v169
	v_rcp_f32_e32 v169, v169
	s_nop 0
	v_mul_f32_e32 v171, 0xbfb8aa3b, v185
	v_exp_f32_e32 v171, v171
	s_nop 0
	v_add_f32_e32 v171, 1.0, v171
	v_rcp_f32_e32 v171, v171
	s_nop 0
	v_mul_f32_e32 v173, 0xbfb8aa3b, v187
	v_exp_f32_e32 v173, v173
	s_nop 0
	v_add_f32_e32 v173, 1.0, v173
	v_rcp_f32_e32 v173, v173
	s_nop 0
	v_mul_f32_e32 v175, 0xbfb8aa3b, v182
	v_exp_f32_e32 v175, v175
	s_nop 0
	v_add_f32_e32 v175, 1.0, v175
	v_rcp_f32_e32 v175, v175
	s_nop 0
	v_rcp_f32_e32 v184, v180
	s_nop 0
	v_mul_f32_e32 v180, 0xbfb8aa3b, v183
	v_exp_f32_e32 v180, v180
	s_nop 0
	v_add_f32_e32 v180, 1.0, v180
	v_rcp_f32_e32 v182, v180
	s_nop 0
	v_mul_f32_e32 v180, 0xbfb8aa3b, v181
	v_exp_f32_e32 v180, v180
	s_nop 0
	v_add_f32_e32 v180, 1.0, v180
	v_rcp_f32_e32 v183, v180
	s_nop 0
	v_cvt_pk_bf16_f32 v180, v0, v171
	v_cvt_pk_bf16_f32 v181, v175, v182
	v_cvt_pk_bf16_f32 v182, v169, v173
	v_cvt_pk_bf16_f32 v183, v184, v183
	global_store_dwordx4 v[178:179], v[180:183], off offset:256
	v_pk_fma_f32 v[178:179], v[100:101], v[170:171], v[108:109] op_sel_hi:[1,0,1]
	v_pk_fma_f32 v[184:185], v[98:99], v[170:171], v[106:107] op_sel_hi:[1,0,1]
	v_pk_fma_f32 v[182:183], v[102:103], v[170:171], v[110:111] op_sel_hi:[1,0,1]
	v_pk_fma_f32 v[180:181], v[104:105], v[170:171], v[112:113] op_sel_hi:[1,0,1]
	v_mul_f32_e32 v0, 0xbfb8aa3b, v182
	v_exp_f32_e32 v0, v0
	v_mul_f32_e32 v178, 0xbfb8aa3b, v178
	v_exp_f32_e32 v178, v178
	v_mul_f32_e32 v179, 0xbfb8aa3b, v179
	v_add_f32_e32 v0, 1.0, v0
	v_add_f32_e32 v178, 1.0, v178
	v_exp_f32_e32 v179, v179
	v_rcp_f32_e32 v0, v0
	s_nop 0
	v_mul_f32_e32 v169, 0xbfb8aa3b, v184
	v_exp_f32_e32 v169, v169
	v_add_f32_e32 v179, 1.0, v179
	v_add_f32_e32 v169, 1.0, v169
	v_rcp_f32_e32 v169, v169
	s_nop 0
	v_mul_f32_e32 v171, 0xbfb8aa3b, v183
	v_exp_f32_e32 v171, v171
	s_nop 0
	v_add_f32_e32 v171, 1.0, v171
	v_rcp_f32_e32 v171, v171
	s_nop 0
	v_mul_f32_e32 v173, 0xbfb8aa3b, v185
	v_exp_f32_e32 v173, v173
	v_pk_fma_f32 v[186:187], v[82:83], v[170:171], v[90:91] op_sel_hi:[1,0,1]
	v_add_f32_e32 v173, 1.0, v173
	v_rcp_f32_e32 v173, v173
	s_nop 0
	v_mul_f32_e32 v175, 0xbfb8aa3b, v180
	v_exp_f32_e32 v175, v175
	s_nop 0
	v_add_f32_e32 v175, 1.0, v175
	v_rcp_f32_e32 v175, v175
	s_nop 0
	v_rcp_f32_e32 v178, v178
	s_nop 0
	v_mul_f32_e32 v180, 0xbfb8aa3b, v181
	v_exp_f32_e32 v180, v180
	s_nop 0
	v_add_f32_e32 v180, 1.0, v180
	v_rcp_f32_e32 v181, v180
	s_nop 0
	s_mov_b64 s[2:3], 0x20000
	v_rcp_f32_e32 v179, v179
	s_nop 0
	v_cvt_pk_bf16_f32 v180, v0, v171
	v_cvt_pk_bf16_f32 v181, v175, v181
	v_cvt_pk_bf16_f32 v182, v169, v173
	v_cvt_pk_bf16_f32 v183, v178, v179
	v_lshl_add_u64 v[178:179], v[176:177], 0, s[2:3]
	s_mov_b32 s2, 0x20000
	v_add_co_u32_e32 v184, vcc, s2, v176
	s_nop 1
	v_addc_co_u32_e32 v185, vcc, 0, v177, vcc
	global_store_dwordx4 v[184:185], v[180:183], off
	v_pk_fma_f32 v[184:185], v[86:87], v[170:171], v[94:95] op_sel_hi:[1,0,1]
	s_nop 0
	v_mul_f32_e32 v0, 0xbfb8aa3b, v184
; __device__ __forceinline__ float sigmoidf_(float x) { return 1.0f / (1.0f + __builtin_amdgcn_exp2f(-1.4426950408889634f * x)); }
; #define EPIIN_PACK(w, a, b) do { (w).x = cvt_pk_bf16((a)[0], (a)[1]); (w).y = cvt_pk_bf16((a)[2], (a)[3]); (w).z = cvt_pk_bf16((b)[0], (b)[1]); (w).w = cvt_pk_bf16((b)[2], (b)[3]); } while (0)
;     __device__ __forceinline__ void operator()(const f32x4 (&acc_)[2][2][4][2], const Unit& u, int wr, int wc, int fr, int fq) const {
;     ...
;         } else {
; #pragma unroll
;             for (int ai = 0; ai < 2; ++ai)
; #pragma unroll
;                 for (int m = 0; m < 4; ++m) { const size_t row = rowb + ai * HALF + m * 16;
; #pragma unroll
;                     for (int bj = 0; bj < 2; ++bj) { f32x4 a = EPIIN_VAL(ai, bj, m, 0), b = EPIIN_VAL(ai, bj, m, 1);
; #pragma unroll
;                         for (int i = 0; i < 4; ++i) { a[i] = sigmoidf_(a[i]); b[i] = sigmoidf_(b[i]); }
;                         u32x4 w; EPIIN_PACK(w, a, b);
;                         *(u32x4*)(GATES + row * 2048 + (pn - 8) * 256 + bj * HALF + wc * 32 + fq * 8) = w; } }
	v_exp_f32_e32 v0, v0
	v_pk_fma_f32 v[182:183], v[88:89], v[170:171], v[96:97] op_sel_hi:[1,0,1]
	v_pk_fma_f32 v[180:181], v[84:85], v[170:171], v[92:93] op_sel_hi:[1,0,1]
	v_add_f32_e32 v0, 1.0, v0
	v_mul_f32_e32 v180, 0xbfb8aa3b, v180
	v_exp_f32_e32 v180, v180
	v_rcp_f32_e32 v0, v0
	s_nop 0
	v_mul_f32_e32 v169, 0xbfb8aa3b, v186
	v_exp_f32_e32 v169, v169
	v_add_f32_e32 v180, 1.0, v180
	v_add_f32_e32 v169, 1.0, v169
	v_rcp_f32_e32 v169, v169
	s_nop 0
	v_mul_f32_e32 v171, 0xbfb8aa3b, v185
	v_exp_f32_e32 v171, v171
	s_nop 0
	v_add_f32_e32 v171, 1.0, v171
	v_rcp_f32_e32 v171, v171
	s_nop 0
	v_mul_f32_e32 v173, 0xbfb8aa3b, v187
	v_exp_f32_e32 v173, v173
	s_nop 0
	v_add_f32_e32 v173, 1.0, v173
	v_rcp_f32_e32 v173, v173
	s_nop 0
	v_mul_f32_e32 v175, 0xbfb8aa3b, v182
	v_exp_f32_e32 v175, v175
	s_nop 0
	v_add_f32_e32 v175, 1.0, v175
	v_rcp_f32_e32 v175, v175
	s_nop 0
	v_rcp_f32_e32 v184, v180
	s_nop 0
	v_mul_f32_e32 v180, 0xbfb8aa3b, v183
	v_exp_f32_e32 v180, v180
	s_nop 0
	v_add_f32_e32 v180, 1.0, v180
	v_rcp_f32_e32 v182, v180
	s_nop 0
	v_mul_f32_e32 v180, 0xbfb8aa3b, v181
	v_exp_f32_e32 v180, v180
	s_nop 0
	v_add_f32_e32 v180, 1.0, v180
	v_rcp_f32_e32 v183, v180
	s_nop 0
	v_cvt_pk_bf16_f32 v180, v0, v171
	v_cvt_pk_bf16_f32 v181, v175, v182
	v_cvt_pk_bf16_f32 v182, v169, v173
	v_cvt_pk_bf16_f32 v183, v184, v183
	global_store_dwordx4 v[178:179], v[180:183], off offset:256
	v_pk_fma_f32 v[178:179], v[76:77], v[168:169], v[108:109] op_sel_hi:[1,0,1]
	v_pk_fma_f32 v[184:185], v[74:75], v[168:169], v[106:107] op_sel_hi:[1,0,1]
	v_pk_fma_f32 v[182:183], v[78:79], v[168:169], v[110:111] op_sel_hi:[1,0,1]
	v_pk_fma_f32 v[180:181], v[80:81], v[168:169], v[112:113] op_sel_hi:[1,0,1]
	v_mul_f32_e32 v0, 0xbfb8aa3b, v182
	v_exp_f32_e32 v0, v0
	v_mul_f32_e32 v178, 0xbfb8aa3b, v178
	v_exp_f32_e32 v178, v178
	v_mul_f32_e32 v179, 0xbfb8aa3b, v179
	v_add_f32_e32 v0, 1.0, v0
	v_add_f32_e32 v178, 1.0, v178
	v_exp_f32_e32 v179, v179
	v_rcp_f32_e32 v0, v0
	s_nop 0
	v_mul_f32_e32 v169, 0xbfb8aa3b, v184
	v_exp_f32_e32 v169, v169
	v_add_f32_e32 v179, 1.0, v179
	v_add_f32_e32 v169, 1.0, v169
	v_rcp_f32_e32 v169, v169
	s_nop 0
	v_mul_f32_e32 v171, 0xbfb8aa3b, v183
	v_exp_f32_e32 v171, v171
	v_pk_fma_f32 v[186:187], v[66:67], v[168:169], v[90:91] op_sel_hi:[1,0,1]
	v_add_f32_e32 v171, 1.0, v171
	v_rcp_f32_e32 v171, v171
	s_nop 0
	v_mul_f32_e32 v173, 0xbfb8aa3b, v185
	v_exp_f32_e32 v173, v173
	s_nop 0
	v_add_f32_e32 v173, 1.0, v173
	v_rcp_f32_e32 v173, v173
	s_nop 0
	v_mul_f32_e32 v175, 0xbfb8aa3b, v180
	v_exp_f32_e32 v175, v175
	s_nop 0
	v_add_f32_e32 v175, 1.0, v175
	v_rcp_f32_e32 v175, v175
	s_nop 0
	v_rcp_f32_e32 v178, v178
	s_nop 0
	v_mul_f32_e32 v180, 0xbfb8aa3b, v181
	v_exp_f32_e32 v180, v180
	s_nop 0
	v_add_f32_e32 v180, 1.0, v180
	v_rcp_f32_e32 v181, v180
	s_nop 0
	s_mov_b64 s[2:3], 0x30000
	v_rcp_f32_e32 v179, v179
	s_nop 0
	v_cvt_pk_bf16_f32 v180, v0, v171
	v_cvt_pk_bf16_f32 v181, v175, v181
	v_cvt_pk_bf16_f32 v182, v169, v173
	v_cvt_pk_bf16_f32 v183, v178, v179
	v_lshl_add_u64 v[178:179], v[176:177], 0, s[2:3]
	s_mov_b32 s2, 0x30000
	v_add_co_u32_e32 v184, vcc, s2, v176
	s_nop 1
	v_addc_co_u32_e32 v185, vcc, 0, v177, vcc
	global_store_dwordx4 v[184:185], v[180:183], off
	v_pk_fma_f32 v[184:185], v[70:71], v[168:169], v[94:95] op_sel_hi:[1,0,1]
	s_nop 0
	v_mul_f32_e32 v0, 0xbfb8aa3b, v184
	v_exp_f32_e32 v0, v0
	v_pk_fma_f32 v[182:183], v[72:73], v[168:169], v[96:97] op_sel_hi:[1,0,1]
	v_pk_fma_f32 v[180:181], v[68:69], v[168:169], v[92:93] op_sel_hi:[1,0,1]
	v_add_f32_e32 v0, 1.0, v0
	v_mul_f32_e32 v180, 0xbfb8aa3b, v180
	v_exp_f32_e32 v180, v180
	v_rcp_f32_e32 v0, v0
	s_nop 0
	v_mul_f32_e32 v169, 0xbfb8aa3b, v186
	v_exp_f32_e32 v169, v169
	v_add_f32_e32 v180, 1.0, v180
	v_add_f32_e32 v169, 1.0, v169
	v_rcp_f32_e32 v169, v169
	s_nop 0
	v_mul_f32_e32 v171, 0xbfb8aa3b, v185
	v_exp_f32_e32 v171, v171
	s_nop 0
	v_add_f32_e32 v171, 1.0, v171
	v_rcp_f32_e32 v171, v171
	s_nop 0
	v_mul_f32_e32 v173, 0xbfb8aa3b, v187
	v_exp_f32_e32 v173, v173
	s_nop 0
	v_add_f32_e32 v173, 1.0, v173
	v_rcp_f32_e32 v173, v173
	s_nop 0
	v_mul_f32_e32 v175, 0xbfb8aa3b, v182
	v_exp_f32_e32 v175, v175
	s_nop 0
	v_add_f32_e32 v175, 1.0, v175
	v_rcp_f32_e32 v175, v175
	s_nop 0
	v_rcp_f32_e32 v184, v180
	s_nop 0
	v_mul_f32_e32 v180, 0xbfb8aa3b, v183
	v_exp_f32_e32 v180, v180
	s_nop 0
	v_add_f32_e32 v180, 1.0, v180
	v_rcp_f32_e32 v182, v180
	s_nop 0
	v_mul_f32_e32 v180, 0xbfb8aa3b, v181
	v_exp_f32_e32 v180, v180
	s_nop 0
	v_add_f32_e32 v180, 1.0, v180
	v_rcp_f32_e32 v183, v180
	s_nop 0
	v_cvt_pk_bf16_f32 v180, v0, v171
	v_cvt_pk_bf16_f32 v181, v175, v182
	v_cvt_pk_bf16_f32 v182, v169, v173
	v_cvt_pk_bf16_f32 v183, v184, v183
	global_store_dwordx4 v[178:179], v[180:183], off offset:256
	v_pk_fma_f32 v[184:185], v[58:59], v[166:167], v[106:107] op_sel_hi:[1,0,1]
	v_pk_fma_f32 v[178:179], v[60:61], v[166:167], v[108:109] op_sel_hi:[1,0,1]
	v_pk_fma_f32 v[182:183], v[62:63], v[166:167], v[110:111] op_sel_hi:[1,0,1]
	v_pk_fma_f32 v[180:181], v[64:65], v[166:167], v[112:113] op_sel_hi:[1,0,1]
	v_mul_f32_e32 v0, 0xbfb8aa3b, v182
	v_exp_f32_e32 v0, v0
	v_mul_f32_e32 v178, 0xbfb8aa3b, v178
	v_exp_f32_e32 v178, v178
	v_mul_f32_e32 v179, 0xbfb8aa3b, v179
	v_add_f32_e32 v0, 1.0, v0
	v_add_f32_e32 v178, 1.0, v178
	v_exp_f32_e32 v179, v179
	v_pk_fma_f32 v[186:187], v[50:51], v[166:167], v[90:91] op_sel_hi:[1,0,1]
	v_rcp_f32_e32 v0, v0
	s_nop 0
	v_mul_f32_e32 v169, 0xbfb8aa3b, v184
	v_exp_f32_e32 v169, v169
	v_add_f32_e32 v179, 1.0, v179
	v_add_f32_e32 v169, 1.0, v169
	v_rcp_f32_e32 v169, v169
	s_nop 0
	v_mul_f32_e32 v171, 0xbfb8aa3b, v183
	v_exp_f32_e32 v171, v171
	s_nop 0
	v_add_f32_e32 v171, 1.0, v171
; __device__ __forceinline__ float sigmoidf_(float x) { return 1.0f / (1.0f + __builtin_amdgcn_exp2f(-1.4426950408889634f * x)); }
; #define EPIIN_PACK(w, a, b) do { (w).x = cvt_pk_bf16((a)[0], (a)[1]); (w).y = cvt_pk_bf16((a)[2], (a)[3]); (w).z = cvt_pk_bf16((b)[0], (b)[1]); (w).w = cvt_pk_bf16((b)[2], (b)[3]); } while (0)
;     __device__ __forceinline__ void operator()(const f32x4 (&acc_)[2][2][4][2], const Unit& u, int wr, int wc, int fr, int fq) const {
;     ...
;         } else {
; #pragma unroll
;             for (int ai = 0; ai < 2; ++ai)
; #pragma unroll
;                 for (int m = 0; m < 4; ++m) { const size_t row = rowb + ai * HALF + m * 16;
; #pragma unroll
;                     for (int bj = 0; bj < 2; ++bj) { f32x4 a = EPIIN_VAL(ai, bj, m, 0), b = EPIIN_VAL(ai, bj, m, 1);
; #pragma unroll
;                         for (int i = 0; i < 4; ++i) { a[i] = sigmoidf_(a[i]); b[i] = sigmoidf_(b[i]); }
;                         u32x4 w; EPIIN_PACK(w, a, b);
;                         *(u32x4*)(GATES + row * 2048 + (pn - 8) * 256 + bj * HALF + wc * 32 + fq * 8) = w; } }
	v_rcp_f32_e32 v171, v171
	s_nop 0
	v_mul_f32_e32 v173, 0xbfb8aa3b, v185
	v_exp_f32_e32 v173, v173
	s_nop 0
	v_add_f32_e32 v173, 1.0, v173
	v_rcp_f32_e32 v173, v173
	s_nop 0
	v_mul_f32_e32 v175, 0xbfb8aa3b, v180
	v_exp_f32_e32 v175, v175
	s_nop 0
	v_add_f32_e32 v175, 1.0, v175
	v_rcp_f32_e32 v175, v175
	s_nop 0
	v_rcp_f32_e32 v178, v178
	s_nop 0
	v_mul_f32_e32 v180, 0xbfb8aa3b, v181
	v_exp_f32_e32 v180, v180
	s_nop 0
	v_add_f32_e32 v180, 1.0, v180
	v_rcp_f32_e32 v181, v180
	s_nop 0
	s_mov_b64 s[2:3], 0x80000
	v_rcp_f32_e32 v179, v179
	s_nop 0
	v_cvt_pk_bf16_f32 v180, v0, v171
	v_cvt_pk_bf16_f32 v181, v175, v181
	v_cvt_pk_bf16_f32 v182, v169, v173
	v_cvt_pk_bf16_f32 v183, v178, v179
	v_lshl_add_u64 v[178:179], v[176:177], 0, s[2:3]
	s_mov_b32 s2, 0x80000
	v_add_co_u32_e32 v184, vcc, s2, v176
	s_nop 1
	v_addc_co_u32_e32 v185, vcc, 0, v177, vcc
	global_store_dwordx4 v[184:185], v[180:183], off
	v_pk_fma_f32 v[184:185], v[54:55], v[166:167], v[94:95] op_sel_hi:[1,0,1]
	s_nop 0
	v_mul_f32_e32 v0, 0xbfb8aa3b, v184
	v_exp_f32_e32 v0, v0
	v_pk_fma_f32 v[182:183], v[56:57], v[166:167], v[96:97] op_sel_hi:[1,0,1]
	v_pk_fma_f32 v[180:181], v[52:53], v[166:167], v[92:93] op_sel_hi:[1,0,1]
	v_add_f32_e32 v0, 1.0, v0
	v_mul_f32_e32 v180, 0xbfb8aa3b, v180
	v_exp_f32_e32 v180, v180
	v_rcp_f32_e32 v0, v0
	s_nop 0
	v_mul_f32_e32 v169, 0xbfb8aa3b, v186
	v_exp_f32_e32 v169, v169
	v_add_f32_e32 v180, 1.0, v180
	v_add_f32_e32 v169, 1.0, v169
	v_rcp_f32_e32 v169, v169
	s_nop 0
	v_mul_f32_e32 v171, 0xbfb8aa3b, v185
	v_exp_f32_e32 v171, v171
	s_nop 0
	v_add_f32_e32 v171, 1.0, v171
	v_rcp_f32_e32 v171, v171
	s_nop 0
	v_mul_f32_e32 v173, 0xbfb8aa3b, v187
	v_exp_f32_e32 v173, v173
	s_nop 0
	v_add_f32_e32 v173, 1.0, v173
	v_rcp_f32_e32 v173, v173
	s_nop 0
	v_mul_f32_e32 v175, 0xbfb8aa3b, v182
	v_exp_f32_e32 v175, v175
	s_nop 0
	v_add_f32_e32 v175, 1.0, v175
	v_rcp_f32_e32 v175, v175
	s_nop 0
	v_rcp_f32_e32 v184, v180
	s_nop 0
	v_mul_f32_e32 v180, 0xbfb8aa3b, v183
	v_exp_f32_e32 v180, v180
	s_nop 0
	v_add_f32_e32 v180, 1.0, v180
	v_rcp_f32_e32 v182, v180
	s_nop 0
	v_mul_f32_e32 v180, 0xbfb8aa3b, v181
	v_exp_f32_e32 v180, v180
	s_nop 0
	v_add_f32_e32 v180, 1.0, v180
	v_rcp_f32_e32 v183, v180
	s_nop 0
	v_cvt_pk_bf16_f32 v180, v0, v171
	v_cvt_pk_bf16_f32 v181, v175, v182
	v_cvt_pk_bf16_f32 v182, v169, v173
	v_cvt_pk_bf16_f32 v183, v184, v183
	global_store_dwordx4 v[178:179], v[180:183], off offset:256
	v_pk_fma_f32 v[184:185], v[42:43], v[164:165], v[106:107] op_sel_hi:[1,0,1]
	v_pk_fma_f32 v[178:179], v[44:45], v[164:165], v[108:109] op_sel_hi:[1,0,1]
	v_pk_fma_f32 v[182:183], v[46:47], v[164:165], v[110:111] op_sel_hi:[1,0,1]
	v_pk_fma_f32 v[180:181], v[48:49], v[164:165], v[112:113] op_sel_hi:[1,0,1]
	v_mul_f32_e32 v0, 0xbfb8aa3b, v182
	v_exp_f32_e32 v0, v0
	v_mul_f32_e32 v178, 0xbfb8aa3b, v178
	v_exp_f32_e32 v178, v178
	v_mul_f32_e32 v179, 0xbfb8aa3b, v179
	v_add_f32_e32 v0, 1.0, v0
	v_add_f32_e32 v178, 1.0, v178
	v_exp_f32_e32 v179, v179
	v_pk_fma_f32 v[186:187], v[34:35], v[164:165], v[90:91] op_sel_hi:[1,0,1]
	v_rcp_f32_e32 v0, v0
	s_nop 0
	v_mul_f32_e32 v169, 0xbfb8aa3b, v184
	v_exp_f32_e32 v169, v169
	v_add_f32_e32 v179, 1.0, v179
	v_add_f32_e32 v169, 1.0, v169
	v_rcp_f32_e32 v169, v169
	s_nop 0
	v_mul_f32_e32 v171, 0xbfb8aa3b, v183
	v_exp_f32_e32 v171, v171
	s_nop 0
	v_add_f32_e32 v171, 1.0, v171
	v_rcp_f32_e32 v171, v171
	s_nop 0
	v_mul_f32_e32 v173, 0xbfb8aa3b, v185
	v_exp_f32_e32 v173, v173
	s_nop 0
	v_add_f32_e32 v173, 1.0, v173
	v_rcp_f32_e32 v173, v173
	s_nop 0
	v_mul_f32_e32 v175, 0xbfb8aa3b, v180
	v_exp_f32_e32 v175, v175
	s_nop 0
	v_add_f32_e32 v175, 1.0, v175
	v_rcp_f32_e32 v175, v175
	s_nop 0
	v_rcp_f32_e32 v178, v178
	s_nop 0
	v_mul_f32_e32 v180, 0xbfb8aa3b, v181
	v_exp_f32_e32 v180, v180
	s_nop 0
	v_add_f32_e32 v180, 1.0, v180
	v_rcp_f32_e32 v181, v180
	s_nop 0
	s_mov_b64 s[2:3], 0x90000
	v_rcp_f32_e32 v179, v179
	s_nop 0
	v_cvt_pk_bf16_f32 v180, v0, v171
	v_cvt_pk_bf16_f32 v181, v175, v181
	v_cvt_pk_bf16_f32 v182, v169, v173
	v_cvt_pk_bf16_f32 v183, v178, v179
	v_lshl_add_u64 v[178:179], v[176:177], 0, s[2:3]
	s_mov_b32 s2, 0x90000
	v_add_co_u32_e32 v184, vcc, s2, v176
	s_nop 1
	v_addc_co_u32_e32 v185, vcc, 0, v177, vcc
	global_store_dwordx4 v[184:185], v[180:183], off
	v_pk_fma_f32 v[184:185], v[38:39], v[164:165], v[94:95] op_sel_hi:[1,0,1]
	s_nop 0
	v_mul_f32_e32 v0, 0xbfb8aa3b, v184
	v_exp_f32_e32 v0, v0
	v_pk_fma_f32 v[182:183], v[40:41], v[164:165], v[96:97] op_sel_hi:[1,0,1]
	v_pk_fma_f32 v[180:181], v[36:37], v[164:165], v[92:93] op_sel_hi:[1,0,1]
	v_add_f32_e32 v0, 1.0, v0
	v_mul_f32_e32 v180, 0xbfb8aa3b, v180
	v_exp_f32_e32 v180, v180
	v_rcp_f32_e32 v0, v0
	s_nop 0
	v_mul_f32_e32 v169, 0xbfb8aa3b, v186
	v_exp_f32_e32 v169, v169
	v_add_f32_e32 v180, 1.0, v180
	v_add_f32_e32 v169, 1.0, v169
	v_rcp_f32_e32 v169, v169
	s_nop 0
	v_mul_f32_e32 v171, 0xbfb8aa3b, v185
	v_exp_f32_e32 v171, v171
	s_nop 0
	v_add_f32_e32 v171, 1.0, v171
	v_rcp_f32_e32 v171, v171
	s_nop 0
	v_mul_f32_e32 v173, 0xbfb8aa3b, v187
	v_exp_f32_e32 v173, v173
	s_nop 0
	v_add_f32_e32 v173, 1.0, v173
	v_rcp_f32_e32 v173, v173
	s_nop 0
	v_mul_f32_e32 v175, 0xbfb8aa3b, v182
	v_exp_f32_e32 v175, v175
	s_nop 0
	v_add_f32_e32 v175, 1.0, v175
	v_rcp_f32_e32 v175, v175
	s_nop 0
	v_rcp_f32_e32 v184, v180
	s_nop 0
	v_mul_f32_e32 v180, 0xbfb8aa3b, v183
	v_exp_f32_e32 v180, v180
	s_nop 0
	v_add_f32_e32 v180, 1.0, v180
	v_rcp_f32_e32 v182, v180
	s_nop 0
	v_mul_f32_e32 v180, 0xbfb8aa3b, v181
	v_exp_f32_e32 v180, v180
	s_nop 0
	v_add_f32_e32 v180, 1.0, v180
	v_rcp_f32_e32 v183, v180
	s_nop 0
	v_cvt_pk_bf16_f32 v180, v0, v171
	v_cvt_pk_bf16_f32 v181, v175, v182
	v_cvt_pk_bf16_f32 v182, v169, v173
; __device__ __forceinline__ float sigmoidf_(float x) { return 1.0f / (1.0f + __builtin_amdgcn_exp2f(-1.4426950408889634f * x)); }
; #define EPIIN_PACK(w, a, b) do { (w).x = cvt_pk_bf16((a)[0], (a)[1]); (w).y = cvt_pk_bf16((a)[2], (a)[3]); (w).z = cvt_pk_bf16((b)[0], (b)[1]); (w).w = cvt_pk_bf16((b)[2], (b)[3]); } while (0)
;     __device__ __forceinline__ void operator()(const f32x4 (&acc_)[2][2][4][2], const Unit& u, int wr, int wc, int fr, int fq) const {
;     ...
;         } else {
; #pragma unroll
;             for (int ai = 0; ai < 2; ++ai)
; #pragma unroll
;                 for (int m = 0; m < 4; ++m) { const size_t row = rowb + ai * HALF + m * 16;
; #pragma unroll
;                     for (int bj = 0; bj < 2; ++bj) { f32x4 a = EPIIN_VAL(ai, bj, m, 0), b = EPIIN_VAL(ai, bj, m, 1);
; #pragma unroll
;                         for (int i = 0; i < 4; ++i) { a[i] = sigmoidf_(a[i]); b[i] = sigmoidf_(b[i]); }
;                         u32x4 w; EPIIN_PACK(w, a, b);
;                         *(u32x4*)(GATES + row * 2048 + (pn - 8) * 256 + bj * HALF + wc * 32 + fq * 8) = w; } }
	v_cvt_pk_bf16_f32 v183, v184, v183
	global_store_dwordx4 v[178:179], v[180:183], off offset:256
	v_pk_fma_f32 v[184:185], v[26:27], v[162:163], v[106:107] op_sel_hi:[1,0,1]
	v_pk_fma_f32 v[178:179], v[28:29], v[162:163], v[108:109] op_sel_hi:[1,0,1]
	v_pk_fma_f32 v[182:183], v[30:31], v[162:163], v[110:111] op_sel_hi:[1,0,1]
	v_pk_fma_f32 v[180:181], v[32:33], v[162:163], v[112:113] op_sel_hi:[1,0,1]
	v_mul_f32_e32 v0, 0xbfb8aa3b, v182
	v_exp_f32_e32 v0, v0
	v_mul_f32_e32 v178, 0xbfb8aa3b, v178
	v_exp_f32_e32 v178, v178
	v_mul_f32_e32 v179, 0xbfb8aa3b, v179
	v_add_f32_e32 v0, 1.0, v0
	v_add_f32_e32 v178, 1.0, v178
	v_exp_f32_e32 v179, v179
	v_pk_fma_f32 v[186:187], v[18:19], v[162:163], v[90:91] op_sel_hi:[1,0,1]
	v_rcp_f32_e32 v0, v0
	s_nop 0
	v_mul_f32_e32 v169, 0xbfb8aa3b, v184
	v_exp_f32_e32 v169, v169
	v_add_f32_e32 v179, 1.0, v179
	v_add_f32_e32 v169, 1.0, v169
	v_rcp_f32_e32 v169, v169
	s_nop 0
	v_mul_f32_e32 v171, 0xbfb8aa3b, v183
	v_exp_f32_e32 v171, v171
	s_nop 0
	v_add_f32_e32 v171, 1.0, v171
	v_rcp_f32_e32 v171, v171
	s_nop 0
	v_mul_f32_e32 v173, 0xbfb8aa3b, v185
	v_exp_f32_e32 v173, v173
	s_nop 0
	v_add_f32_e32 v173, 1.0, v173
	v_rcp_f32_e32 v173, v173
	s_nop 0
	v_mul_f32_e32 v175, 0xbfb8aa3b, v180
	v_exp_f32_e32 v175, v175
	s_nop 0
	v_add_f32_e32 v175, 1.0, v175
	v_rcp_f32_e32 v175, v175
	s_nop 0
	v_rcp_f32_e32 v178, v178
	s_nop 0
	v_mul_f32_e32 v180, 0xbfb8aa3b, v181
	v_exp_f32_e32 v180, v180
	s_nop 0
	v_add_f32_e32 v180, 1.0, v180
	v_rcp_f32_e32 v181, v180
	s_nop 0
	s_mov_b64 s[2:3], 0xa0000
	v_rcp_f32_e32 v179, v179
	s_nop 0
	v_cvt_pk_bf16_f32 v180, v0, v171
	v_cvt_pk_bf16_f32 v181, v175, v181
	v_cvt_pk_bf16_f32 v182, v169, v173
	v_cvt_pk_bf16_f32 v183, v178, v179
	v_lshl_add_u64 v[178:179], v[176:177], 0, s[2:3]
	s_mov_b32 s2, 0xa0000
	v_add_co_u32_e32 v184, vcc, s2, v176
	s_nop 1
	v_addc_co_u32_e32 v185, vcc, 0, v177, vcc
	global_store_dwordx4 v[184:185], v[180:183], off
	v_pk_fma_f32 v[184:185], v[22:23], v[162:163], v[94:95] op_sel_hi:[1,0,1]
	s_nop 0
	v_mul_f32_e32 v0, 0xbfb8aa3b, v184
	v_exp_f32_e32 v0, v0
	v_pk_fma_f32 v[182:183], v[24:25], v[162:163], v[96:97] op_sel_hi:[1,0,1]
	v_pk_fma_f32 v[180:181], v[20:21], v[162:163], v[92:93] op_sel_hi:[1,0,1]
	v_add_f32_e32 v0, 1.0, v0
	v_mul_f32_e32 v180, 0xbfb8aa3b, v180
	v_exp_f32_e32 v180, v180
	v_rcp_f32_e32 v0, v0
	s_nop 0
	v_mul_f32_e32 v169, 0xbfb8aa3b, v186
	v_exp_f32_e32 v169, v169
	v_add_f32_e32 v180, 1.0, v180
	v_add_f32_e32 v169, 1.0, v169
	v_rcp_f32_e32 v169, v169
	s_nop 0
	v_mul_f32_e32 v171, 0xbfb8aa3b, v185
	v_exp_f32_e32 v171, v171
	s_nop 0
	v_add_f32_e32 v171, 1.0, v171
	v_rcp_f32_e32 v171, v171
	s_nop 0
	v_mul_f32_e32 v173, 0xbfb8aa3b, v187
	v_exp_f32_e32 v173, v173
	s_nop 0
	v_add_f32_e32 v173, 1.0, v173
	v_rcp_f32_e32 v173, v173
	s_nop 0
	v_mul_f32_e32 v175, 0xbfb8aa3b, v182
	v_exp_f32_e32 v175, v175
	s_nop 0
	v_add_f32_e32 v175, 1.0, v175
	v_rcp_f32_e32 v175, v175
	s_nop 0
	v_rcp_f32_e32 v184, v180
	s_nop 0
	v_mul_f32_e32 v180, 0xbfb8aa3b, v183
	v_exp_f32_e32 v180, v180
	s_nop 0
	v_add_f32_e32 v180, 1.0, v180
	v_rcp_f32_e32 v182, v180
	s_nop 0
	v_mul_f32_e32 v180, 0xbfb8aa3b, v181
	v_exp_f32_e32 v180, v180
	s_nop 0
	v_add_f32_e32 v180, 1.0, v180
	v_rcp_f32_e32 v183, v180
	s_nop 0
	v_cvt_pk_bf16_f32 v180, v0, v171
	v_cvt_pk_bf16_f32 v181, v175, v182
	v_cvt_pk_bf16_f32 v182, v169, v173
	v_cvt_pk_bf16_f32 v183, v184, v183
	global_store_dwordx4 v[178:179], v[180:183], off offset:256
	v_pk_fma_f32 v[184:185], v[10:11], v[160:161], v[106:107] op_sel_hi:[1,0,1]
	v_pk_fma_f32 v[178:179], v[12:13], v[160:161], v[108:109] op_sel_hi:[1,0,1]
	v_pk_fma_f32 v[182:183], v[14:15], v[160:161], v[110:111] op_sel_hi:[1,0,1]
	v_pk_fma_f32 v[180:181], v[16:17], v[160:161], v[112:113] op_sel_hi:[1,0,1]
	v_mul_f32_e32 v0, 0xbfb8aa3b, v182
	v_exp_f32_e32 v0, v0
	v_mul_f32_e32 v178, 0xbfb8aa3b, v178
	v_exp_f32_e32 v178, v178
	v_mul_f32_e32 v179, 0xbfb8aa3b, v179
	v_add_f32_e32 v0, 1.0, v0
	v_add_f32_e32 v178, 1.0, v178
	v_exp_f32_e32 v179, v179
	v_rcp_f32_e32 v0, v0
	s_nop 0
	v_mul_f32_e32 v169, 0xbfb8aa3b, v184
	v_exp_f32_e32 v169, v169
	v_add_f32_e32 v179, 1.0, v179
	v_add_f32_e32 v169, 1.0, v169
	v_rcp_f32_e32 v169, v169
	s_nop 0
	v_mul_f32_e32 v171, 0xbfb8aa3b, v183
	v_exp_f32_e32 v171, v171
	s_nop 0
	v_add_f32_e32 v171, 1.0, v171
	v_rcp_f32_e32 v171, v171
	s_nop 0
	v_mul_f32_e32 v173, 0xbfb8aa3b, v185
	v_exp_f32_e32 v173, v173
	s_nop 0
	v_add_f32_e32 v173, 1.0, v173
	v_rcp_f32_e32 v173, v173
	s_nop 0
	v_mul_f32_e32 v175, 0xbfb8aa3b, v180
	v_exp_f32_e32 v175, v175
	s_nop 0
	v_add_f32_e32 v175, 1.0, v175
	v_rcp_f32_e32 v175, v175
	s_nop 0
	v_rcp_f32_e32 v178, v178
	s_nop 0
	v_mul_f32_e32 v180, 0xbfb8aa3b, v181
	v_exp_f32_e32 v180, v180
	s_nop 0
	v_add_f32_e32 v180, 1.0, v180
	v_rcp_f32_e32 v181, v180
	s_nop 0
	s_mov_b64 s[2:3], 0xb0000
	v_rcp_f32_e32 v179, v179
	s_nop 0
	v_cvt_pk_bf16_f32 v180, v0, v171
	v_cvt_pk_bf16_f32 v181, v175, v181
	v_cvt_pk_bf16_f32 v182, v169, v173
	v_cvt_pk_bf16_f32 v183, v178, v179
	v_lshl_add_u64 v[178:179], v[176:177], 0, s[2:3]
	s_mov_b32 s2, 0xb0000
	v_add_co_u32_e32 v176, vcc, s2, v176
	v_pk_fma_f32 v[184:185], v[2:3], v[160:161], v[90:91] op_sel_hi:[1,0,1]
	s_nop 0
	v_addc_co_u32_e32 v177, vcc, 0, v177, vcc
	global_store_dwordx4 v[176:177], v[180:183], off
	v_pk_fma_f32 v[176:177], v[4:5], v[160:161], v[92:93] op_sel_hi:[1,0,1]
	s_nop 0
	v_pk_fma_f32 v[182:183], v[6:7], v[160:161], v[94:95] op_sel_hi:[1,0,1]
	v_pk_fma_f32 v[180:181], v[8:9], v[160:161], v[96:97] op_sel_hi:[1,0,1]
	v_mul_f32_e32 v0, 0xbfb8aa3b, v182
	v_exp_f32_e32 v0, v0
	v_mul_f32_e32 v176, 0xbfb8aa3b, v176
	v_exp_f32_e32 v176, v176
	v_mul_f32_e32 v177, 0xbfb8aa3b, v177
	v_add_f32_e32 v0, 1.0, v0
	v_add_f32_e32 v176, 1.0, v176
	v_exp_f32_e32 v177, v177
	v_rcp_f32_e32 v0, v0
	s_nop 0
	v_mul_f32_e32 v169, 0xbfb8aa3b, v184
	v_exp_f32_e32 v169, v169
	v_add_f32_e32 v177, 1.0, v177
	v_add_f32_e32 v169, 1.0, v169
	v_rcp_f32_e32 v169, v169
	s_nop 0
	v_mul_f32_e32 v171, 0xbfb8aa3b, v183
	v_exp_f32_e32 v171, v171
	s_nop 0
	v_add_f32_e32 v171, 1.0, v171
	v_rcp_f32_e32 v171, v171
	s_nop 0
	v_mul_f32_e32 v173, 0xbfb8aa3b, v185
	v_exp_f32_e32 v173, v173
	s_nop 0
	v_add_f32_e32 v173, 1.0, v173
	v_rcp_f32_e32 v173, v173
	s_nop 0
	v_mul_f32_e32 v175, 0xbfb8aa3b, v180
	v_exp_f32_e32 v175, v175
	s_nop 0
	v_add_f32_e32 v175, 1.0, v175
	v_rcp_f32_e32 v175, v175
	s_nop 0
	v_rcp_f32_e32 v176, v176
	s_nop 0
	v_mul_f32_e32 v180, 0xbfb8aa3b, v181
	v_exp_f32_e32 v180, v180
	s_nop 0
	v_add_f32_e32 v180, 1.0, v180
	v_rcp_f32_e32 v181, v180
	s_nop 0
	s_mov_b64 s[2:3], 0
	v_rcp_f32_e32 v177, v177
	s_nop 0
	v_cvt_pk_bf16_f32 v180, v0, v171
	v_cvt_pk_bf16_f32 v181, v175, v181
	v_cvt_pk_bf16_f32 v182, v169, v173
	v_cvt_pk_bf16_f32 v183, v176, v177
	global_store_dwordx4 v[178:179], v[180:183], off offset:256
